# expert-table slice rows stored as one full 128-byte line part + one 64-byte part (loads no longer straddle lines); producer stores and P11/P13 loads re-addressed
# speedup vs baseline: 1.0145x; 1.0063x over previous
; DI const float* inp(int i) { return as_global<const float>(ld_ptr(i)); }
; DI void phase_convert(int l, int wv, bool tables) {
;     ...
;     { const float* pu = inp(I_PU) + (size_t)l * NEXP * D; const float* pv = inp(I_PV) + (size_t)l * NEXP * D;
;       unsigned char* U6 = (unsigned char*)F.U; unsigned char* V6 = (unsigned char*)F.V; float* SU = (float*)(F.ws + WS_ESCALE); float* SV = SU + NEXP;
;       if (tables) for (int it = gw; it < 2 * NEXP; it += NGW) {
;           const int e = it >> 1; const float* src = ((it & 1) ? pv : pu) + (size_t)e * D; unsigned char* dst = (it & 1) ? V6 : U6;
.LBB0_98:
	v_readlane_b32 s0, v253, 62
	s_cmpk_eq_i32 s6, 0x100
	s_nop 0
	v_mov_b32_e32 v0, s0
	v_readlane_b32 s0, v253, 63
	ds_read_b64 v[0:1], v0
	s_waitcnt lgkmcnt(0)
	v_readfirstlane_b32 s7, v1
	v_mov_b32_e32 v2, s0
	ds_read_b64 v[2:3], v2
	s_cselect_b64 s[0:1], -1, 0
	s_cmpk_gt_i32 s16, 0x7fff
	s_cselect_b64 s[12:13], -1, 0
	s_or_b64 s[0:1], s[0:1], s[12:13]
	v_readfirstlane_b32 s8, v0
	s_waitcnt lgkmcnt(0)
	v_readfirstlane_b32 s9, v3
	v_readfirstlane_b32 s10, v2
	s_and_b64 vcc, exec, s[0:1]
	s_cbranch_vccnz .LBB0_103
	s_lshl_b64 s[12:13], s[92:93], 27
	s_bitcmp0_b32 s18, 0
	s_cselect_b32 s7, s7, s9
	s_mov_b32 s9, 0x4c00000
	s_cselect_b32 s8, s8, s10
	s_cselect_b32 s76, s9, 0x8c00000
	s_mov_b32 s9, 0x4b00000
	v_lshlrev_b32_e32 v0, 2, v34
	s_cselect_b32 s10, s9, 0x4b10000
	s_add_u32 s8, s8, s12
	v_ashrrev_i32_e32 v1, 31, v0
	v_and_b32_e32 v2, 64, v239
	s_addc_u32 s9, s7, s13
	v_add_u32_e32 v4, 64, v2
	v_lshl_add_u64 v[18:19], v[0:1], 2, s[8:9]
	v_xor_b32_e32 v0, 1, v239
	v_cmp_lt_i32_e32 vcc, v0, v4
	v_mov_b64_e32 v[2:3], s[2:3]
	v_mad_i64_i32 v[2:3], s[0:1], v35, s50, v[2:3]
	v_cndmask_b32_e32 v0, v239, v0, vcc
	v_lshlrev_b32_e32 v22, 2, v0
	v_xor_b32_e32 v0, 2, v239
	v_cmp_lt_i32_e32 vcc, v0, v4
	v_and_b32_e32 v5, 7, v34
	v_lshlrev_b32_e32 v128, 4, v5
	v_cndmask_b32_e32 v0, v239, v0, vcc
	v_lshlrev_b32_e32 v23, 2, v0
	v_xor_b32_e32 v0, 4, v239
	v_cmp_lt_i32_e32 vcc, v0, v4
	s_add_u32 s7, s2, s10
	v_cmp_eq_u32_e64 s[0:1], 0, v34
	v_cndmask_b32_e32 v0, v239, v0, vcc
	v_lshlrev_b32_e32 v24, 2, v0
	v_xor_b32_e32 v0, 8, v239
	v_cmp_lt_i32_e32 vcc, v0, v4
	s_addc_u32 s10, s3, 0
	s_nop 0
	v_cndmask_b32_e32 v0, v239, v0, vcc
	v_lshlrev_b32_e32 v25, 2, v0
	v_xor_b32_e32 v0, 16, v239
	v_cmp_lt_i32_e32 vcc, v0, v4
	s_nop 1
	v_cndmask_b32_e32 v0, v239, v0, vcc
	v_lshlrev_b32_e32 v26, 2, v0
	v_xor_b32_e32 v0, 32, v239
	v_cmp_lt_i32_e32 vcc, v0, v4
	s_nop 1
	v_cndmask_b32_e32 v0, v239, v0, vcc
	v_lshlrev_b32_e32 v27, 2, v0
	v_lshl_add_u64 v[0:1], v[2:3], 0, s[76:77]
	v_lshl_add_u64 v[20:21], v[0:1], 0, v[128:129]
	s_branch .LBB0_101

; DI void phase_convert(int l, int wv, bool tables) {
;     ...
;       if (tables) for (int it = gw; it < 2 * NEXP; it += NGW) {
;           const int e = it >> 1; const float* src = ((it & 1) ? pv : pu) + (size_t)e * D; unsigned char* dst = (it & 1) ? V6 : U6;
;           f32x4 x[8]; float am = 0.f;
; #pragma unroll
;           for (int c = 0; c < 8; ++c) { x[c] = __builtin_nontemporal_load((const f32x4*)(src + c * 256 + F.lane * 4));
;               am = fmaxf(am, fmaxf(fmaxf(fabsf(x[c].x), fabsf(x[c].y)), fmaxf(fabsf(x[c].z), fabsf(x[c].w)))); }
; #pragma unroll
;           for (int o = 1; o < 64; o <<= 1) am = fmaxf(am, __shfl_xor(am, o));
;           const float inv = am > 0.f ? 7.0f / am : 0.f, sc = am > 0.f ? am * (1.0f / 7.0f) : 0.f;
;           v32h hx;
; #pragma unroll
;           for (int c = 0; c < 8; ++c) { hx[c * 4 + 0] = (_Float16)(x[c].x * inv); hx[c * 4 + 1] = (_Float16)(x[c].y * inv); hx[c * 4 + 2] = (_Float16)(x[c].z * inv); hx[c * 4 + 3] = (_Float16)(x[c].w * inv); }
;           const v6i p = __builtin_amdgcn_cvt_scalef32_pk32_fp6_f16(hx, 1.0f);
;           eseg_store(dst, e, F.lane, p);
;           if (F.lane == 0) ((it & 1) ? SV : SU)[e] = sc;
.LBB0_101:
	s_ashr_i32 s2, s16, 1
	s_ashr_i32 s3, s2, 31
	s_lshl_b64 s[8:9], s[2:3], 13
	v_lshl_add_u64 v[12:13], v[18:19], 0, s[8:9]
	global_load_dwordx4 v[0:3], v[12:13], off nt
	global_load_dwordx4 v[4:7], v[12:13], off offset:1024 nt
	global_load_dwordx4 v[8:11], v[12:13], off offset:2048 nt
	global_load_dwordx4 v[28:31], v[12:13], off offset:3072 nt
	v_add_co_u32_e32 v12, vcc, s61, v12
	s_mov_b32 s11, 0x40e00000
	s_nop 0
	v_addc_co_u32_e32 v13, vcc, 0, v13, vcc
	global_load_dwordx4 v[32:35], v[12:13], off nt
	global_load_dwordx4 v[36:39], v[12:13], off offset:1024 nt
	global_load_dwordx4 v[40:43], v[12:13], off offset:2048 nt
	global_load_dwordx4 v[14:17], v[12:13], off offset:3072 nt
	s_waitcnt vmcnt(7)
	v_max_f32_e64 v12, |v3|, |v3|
	v_max_f32_e64 v13, |v2|, |v2|
	s_waitcnt vmcnt(6)
	v_max_f32_e64 v44, |v7|, |v7|
	v_max_f32_e64 v45, |v6|, |v6|
	s_waitcnt vmcnt(5)
	v_max_f32_e64 v46, |v11|, |v11|
	v_max_f32_e64 v47, |v10|, |v10|
	s_waitcnt vmcnt(4)
	v_max_f32_e64 v48, |v31|, |v31|
	v_max_f32_e64 v49, |v30|, |v30|
	v_max_f32_e32 v12, v13, v12
	v_max_f32_e32 v13, v45, v44
	v_max_f32_e32 v44, v47, v46
	v_max_f32_e32 v45, v49, v48
	s_waitcnt vmcnt(3)
	v_max_f32_e64 v46, |v35|, |v35|
	v_max_f32_e64 v47, |v34|, |v34|
	s_waitcnt vmcnt(2)
	v_max_f32_e64 v48, |v39|, |v39|
	v_max_f32_e64 v49, |v38|, |v38|
	v_max3_f32 v12, |v0|, |v1|, v12
	v_max3_f32 v13, |v4|, |v5|, v13
	s_waitcnt vmcnt(1)
	v_max_f32_e64 v50, |v43|, |v43|
	v_max_f32_e64 v51, |v42|, |v42|
	s_waitcnt vmcnt(0)
	v_max_f32_e64 v52, |v17|, |v17|
	v_max_f32_e64 v53, |v16|, |v16|
	v_max3_f32 v44, |v8|, |v9|, v44
	v_max3_f32 v45, |v28|, |v29|, v45
	v_max_f32_e32 v46, v47, v46
	v_max_f32_e32 v47, v49, v48
	v_max3_f32 v12, v12, 0, v13
	v_max_f32_e32 v48, v51, v50
	v_max_f32_e32 v49, v53, v52
	v_max3_f32 v13, |v32|, |v33|, v46
	v_max3_f32 v46, |v36|, |v37|, v47
	v_max3_f32 v12, v12, v44, v45
	v_max3_f32 v47, |v40|, |v41|, v48
	v_max3_f32 v48, |v14|, |v15|, v49
	v_max3_f32 v12, v12, v13, v46
	v_max3_f32 v12, v12, v47, v48
	ds_bpermute_b32 v13, v22, v12
	s_waitcnt lgkmcnt(0)
	v_max_f32_e32 v13, v13, v13
	v_max_f32_e32 v44, v12, v13
	ds_bpermute_b32 v45, v23, v44
	v_mov_b32_e32 v12, v1
	v_mov_b32_e32 v13, v2
	v_pk_mov_b32 v[2:3], v[2:3], v[4:5] op_sel:[1,0]
	v_mov_b32_e32 v4, v5
	s_waitcnt lgkmcnt(0)
	v_max_f32_e32 v1, v45, v45
	v_max_f32_e32 v1, v44, v1
	ds_bpermute_b32 v44, v24, v1
	v_mov_b32_e32 v5, v6
	v_pk_mov_b32 v[6:7], v[6:7], v[8:9] op_sel:[1,0]
	v_mov_b32_e32 v8, v9
	v_mov_b32_e32 v9, v10
	s_waitcnt lgkmcnt(0)
	v_max_f32_e32 v10, v44, v44
	v_max_f32_e32 v1, v1, v10
	ds_bpermute_b32 v46, v25, v1
	v_pk_mov_b32 v[10:11], v[10:11], v[28:29] op_sel:[1,0]
	v_mov_b32_e32 v44, v29
	v_mov_b32_e32 v45, v30
	v_pk_mov_b32 v[30:31], v[30:31], v[32:33] op_sel:[1,0]
	s_waitcnt lgkmcnt(0)
	v_max_f32_e32 v28, v46, v46
	v_max_f32_e32 v1, v1, v28
	ds_bpermute_b32 v28, v26, v1
	v_mov_b32_e32 v32, v33
	v_mov_b32_e32 v33, v34
	v_pk_mov_b32 v[34:35], v[34:35], v[36:37] op_sel:[1,0]
	v_mov_b32_e32 v36, v37
	s_waitcnt lgkmcnt(0)
	v_max_f32_e32 v28, v28, v28
	v_max_f32_e32 v1, v1, v28
	ds_bpermute_b32 v28, v27, v1
	v_mov_b32_e32 v37, v38
	v_pk_mov_b32 v[38:39], v[38:39], v[40:41] op_sel:[1,0]
	v_mov_b32_e32 v40, v41
	v_mov_b32_e32 v41, v42
	s_waitcnt lgkmcnt(0)
	v_max_f32_e32 v28, v28, v28
	v_max_f32_e32 v28, v1, v28
	v_div_scale_f32 v1, s[8:9], v28, v28, s11
	v_rcp_f32_e32 v29, v1
	v_pk_mov_b32 v[42:43], v[42:43], v[14:15] op_sel:[1,0]
	v_div_scale_f32 v14, vcc, s11, v28, s11
	v_fma_f32 v46, -v1, v29, 1.0
	v_fmac_f32_e32 v29, v46, v29
	v_mul_f32_e32 v46, v14, v29
	v_fma_f32 v47, -v1, v46, v14
	v_fmac_f32_e32 v46, v47, v29
	v_fma_f32 v1, -v1, v46, v14
	v_div_fmas_f32 v1, v1, v29, v46
	v_div_fixup_f32 v1, v1, v28, s11
	v_cmp_lt_f32_e32 vcc, 0, v28
	s_nop 1
	v_cndmask_b32_e32 v46, 0, v1, vcc
	v_fma_mixlo_f16 v14, v0, v46, 0
	v_pk_mul_f32 v[0:1], v[12:13], v[46:47] op_sel_hi:[1,0]
	v_pk_mul_f32 v[42:43], v[42:43], v[46:47] op_sel_hi:[1,0]
	v_cvt_pk_f16_f32 v1, v0, v1
	v_pack_b32_f16 v0, v14, v1
	v_mov_b32_e32 v14, v15
	v_mov_b32_e32 v15, v16
	v_pk_mul_f32 v[14:15], v[14:15], v[46:47] op_sel_hi:[1,0]
	v_pk_mul_f32 v[2:3], v[2:3], v[46:47] op_sel_hi:[1,0]
	v_pk_mul_f32 v[4:5], v[4:5], v[46:47] op_sel_hi:[1,0]
	v_pk_mul_f32 v[6:7], v[6:7], v[46:47] op_sel_hi:[1,0]
	v_pk_mul_f32 v[8:9], v[8:9], v[46:47] op_sel_hi:[1,0]
	v_pk_mul_f32 v[10:11], v[10:11], v[46:47] op_sel_hi:[1,0]
	v_pk_mul_f32 v[12:13], v[44:45], v[46:47] op_sel_hi:[1,0]
	v_pk_mul_f32 v[30:31], v[30:31], v[46:47] op_sel_hi:[1,0]
	v_pk_mul_f32 v[32:33], v[32:33], v[46:47] op_sel_hi:[1,0]
	v_pk_mul_f32 v[34:35], v[34:35], v[46:47] op_sel_hi:[1,0]
	v_pk_mul_f32 v[36:37], v[36:37], v[46:47] op_sel_hi:[1,0]
	v_pk_mul_f32 v[38:39], v[38:39], v[46:47] op_sel_hi:[1,0]
	v_pk_mul_f32 v[40:41], v[40:41], v[46:47] op_sel_hi:[1,0]
	v_cvt_pk_f16_f32 v29, v42, v43
	v_cvt_pk_f16_f32 v15, v14, v15
	v_cvt_pk_f16_f32 v2, v2, v3
	v_cvt_pk_f16_f32 v3, v4, v5
	v_cvt_pk_f16_f32 v4, v6, v7
	v_cvt_pk_f16_f32 v5, v8, v9
	v_cvt_pk_f16_f32 v6, v10, v11
	v_cvt_pk_f16_f32 v7, v12, v13
	v_cvt_pk_f16_f32 v8, v30, v31
	v_cvt_pk_f16_f32 v9, v32, v33
	v_cvt_pk_f16_f32 v10, v34, v35
	v_cvt_pk_f16_f32 v11, v36, v37
	v_cvt_pk_f16_f32 v12, v38, v39
	v_cvt_pk_f16_f32 v13, v40, v41
	v_alignbit_b32 v14, v15, v29, 16
	v_lshrrev_b32_e32 v15, 16, v15
	v_alignbit_b32 v1, v2, v1, 16
	v_alignbit_b32 v2, v3, v2, 16
	v_alignbit_b32 v3, v4, v3, 16
	v_alignbit_b32 v4, v5, v4, 16
	v_alignbit_b32 v5, v6, v5, 16
	v_alignbit_b32 v6, v7, v6, 16
	v_alignbit_b32 v7, v8, v7, 16
	v_alignbit_b32 v8, v9, v8, 16
	v_alignbit_b32 v9, v10, v9, 16
	v_alignbit_b32 v10, v11, v10, 16
	v_alignbit_b32 v11, v12, v11, 16
	v_alignbit_b32 v12, v13, v12, 16
	v_alignbit_b32 v13, v29, v13, 16
	v_fma_mixhi_f16 v15, v17, v46, 0
	v_cvt_scalef32_pk32_fp6_f16 v[30:35], v[0:15], 1.0
	s_lshl_b32 s8, s2, 7
	s_mov_b32 s9, 0
	v_lshl_add_u64 v[0:1], v[20:21], 0, s[8:9]
	global_store_dwordx4 v[0:1], v[30:33], off
	v_and_b32_e32 v2, 7, v239
	s_lshl_b32 s8, s2, 6
	v_lshlrev_b32_e32 v2, 3, v2
	s_sub_u32 s8, 0x200000, s8
	v_mov_b32_e32 v3, 0
	v_sub_u32_e32 v2, s8, v2
	v_lshl_add_u64 v[2:3], v[0:1], 0, v[2:3]
	global_store_dwordx2 v[2:3], v[34:35], off
	s_and_saveexec_b64 s[8:9], s[0:1]
	s_cbranch_execz .LBB0_100
	s_lshl_b64 s[2:3], s[2:3], 2
	s_add_u32 s2, s7, s2
	v_mul_f32_e32 v0, 0x3e124925, v28
	s_addc_u32 s3, s10, s3
	v_cndmask_b32_e32 v0, 0, v0, vcc
	global_store_dword v129, v0, s[2:3]
	s_branch .LBB0_100

; #define LAS __attribute__((address_space(3)))
; DI const float* inp(int i) { return as_global<const float>(ld_ptr(i)); }
; DI void phase_scan(int l, int wv, bool fill, bool last) {
;     const Frame F = mkframe(wv);
;     const float* pu = inp(I_PU) + (size_t)l * NEXP * D; const float* pv = inp(I_PV) + (size_t)l * NEXP * D;
;     constexpr int RS = 272, RS64 = 144;
;     constexpr int O_QT = 0, O_KT = 17408, O_ST = 34816, O_V = 52224, O_PM = 61440, O_EV = 70656;
;     LAS unsigned char* L = F.lds;
;     const int tid = F.tid, lane = F.lane, w = F.wave, r32 = lane & 31, hh = lane >> 5;
;     const int srow = tid >> 3, sc16 = (tid & 7) * 16, svc = (tid & 7) * 8;
;     for (int task = blockIdx.x; task < NBATCH * NH * 4; task += F.G) {
;         const int b = task >> 5, h = (task >> 2) & 7, dir = (task >> 1) & 1, vh = task & 1;
;         const int cq = (dir ? C_QTB : C_QTF) + h * DK + sc16, ck = (dir ? C_KTB : C_KTF) + h * DK + sc16, cvv = C_VI + h * DK + vh * 64 + svc;
;         f32x16 S;
; #pragma unroll
;         for (int i = 0; i < 16; ++i) S[i] = 0.f;
;         auto chunk_row0 = [&](int c) { return c < 4 ? NLAT + b * CTXL + (dir ? 3 - c : c) * 64 : b * SEQ + (dir ? 35 - c : c - 4) * 64; };
;         u32x4 q0, q1, k0, k1, vr; f32x4 evr = (f32x4){0.f, 0.f, 0.f, 0.f};
;         f32x4 fx[8]; const int fidx = (int)blockIdx.x * 4 + w; const bool filler = fill && w < 4;
;         auto fill_load = [&](int it) { const float* src = ((it & 1) ? pv : pu) + (size_t)(it >> 1) * D; const float* src2 = src + 1024;
;             unsigned lo = (unsigned)lane * 4u; asm volatile("" : "+v"(lo));
; #pragma unroll
;             for (int c8 = 0; c8 < 4; ++c8) { fx[c8] = __builtin_nontemporal_load((const f32x4*)(src + lo + c8 * 256)); fx[4 + c8] = __builtin_nontemporal_load((const f32x4*)(src2 + lo + c8 * 256)); } };
.LBB0_470:
	s_andn2_b64 vcc, exec, s[0:1]
	s_cbranch_vccnz .LBB0_562
	s_waitcnt vmcnt(0)
	v_mov_b32_e32 v0, v129
	v_readlane_b32 s0, v253, 54
	v_mbcnt_lo_u32_b32 v0, -1, v0
	v_mbcnt_hi_u32_b32 v1, -1, v0
	s_mov_b32 s2, s88
	v_mov_b32_e32 v0, s0
	ds_read_b64 v[2:3], v0
	v_mov_b32_e32 v0, s79
	v_readlane_b32 s0, v253, 62
	s_waitcnt lgkmcnt(0)
	ds_read_b64 v[2:3], v0
	v_readlane_b32 s6, v253, 31
	v_mov_b32_e32 v0, s0
	v_readlane_b32 s0, v253, 63
	ds_read_b64 v[4:5], v0
	v_writelane_b32 v254, s92, 36
	v_mov_b32_e32 v0, s0
	ds_read_b64 v[6:7], v0
	v_readlane_b32 s7, v253, 32
	v_writelane_b32 v254, s93, 37
	s_waitcnt lgkmcnt(2)
	v_readfirstlane_b32 s1, v3
	v_readfirstlane_b32 s0, v2
	s_waitcnt lgkmcnt(1)
	v_readfirstlane_b32 s3, v5
	v_readfirstlane_b32 s4, v4
	s_waitcnt lgkmcnt(0)
	v_readfirstlane_b32 s5, v7
	s_andn2_b64 vcc, exec, s[6:7]
	v_readfirstlane_b32 s6, v6
	s_cbranch_vccnz .LBB0_509
	v_readlane_b32 s8, v254, 28
	v_readlane_b32 s9, v254, 29
	s_load_dword s7, s[8:9], 0x0
	s_add_u32 s48, s0, 0x1ec00000
	s_addc_u32 s49, s1, 0
	s_add_u32 s8, s0, 0x39c00000
	v_writelane_b32 v254, s8, 38
	s_addc_u32 s8, s1, 0
	v_writelane_b32 v254, s8, 39
	s_waitcnt lgkmcnt(0)
	v_writelane_b32 v254, s7, 40
	s_cmpk_eq_i32 s7, 0x100
	v_readlane_b32 s10, v254, 36
	v_readlane_b32 s7, v253, 27
	s_cselect_b64 s[8:9], -1, 0
	s_lshl_b32 s76, s10, 25
	s_add_i32 s67, s2, s7
	s_cmp_lt_i32 s2, 4
	s_cselect_b64 s[54:55], -1, 0
	s_and_b64 s[56:57], s[8:9], s[54:55]
	s_and_b32 s7, s2, 1
	s_lshl_b64 s[8:9], s[76:77], 2
	s_cmp_eq_u32 s7, 0
	s_cselect_b32 s3, s3, s5
	s_cselect_b32 s4, s4, s6
	s_mov_b32 s5, 0x4c00000
	s_cselect_b32 s6, s5, 0x8c00000
	s_add_u32 s68, s4, s8
	s_addc_u32 s69, s3, s9
	s_ashr_i32 s4, s67, 1
	s_ashr_i32 s5, s4, 31
	s_lshl_b64 s[4:5], s[4:5], 13
	s_add_u32 s4, s68, s4
	s_addc_u32 s5, s69, s5
	v_readlane_b32 s11, v254, 37
	s_add_u32 s8, s4, 0x1000
	v_writelane_b32 v254, s4, 41
	s_addc_u32 s9, s5, 0
	v_lshl_add_u32 v4, s2, 6, v1
	v_writelane_b32 v254, s5, 42
	v_writelane_b32 v254, s8, 43
	s_movk_i32 s3, 0x60
	v_cmp_gt_i32_e64 s[36:37], s3, v4
	v_writelane_b32 v254, s9, 44
	s_lshl_b32 s8, s2, 4
	s_movk_i32 s3, 0x5f
	s_and_b32 s9, s8, 0xffffffe0
	v_cmp_lt_i32_e64 s[4:5], s3, v4
	s_lshl_b32 s3, s9, 2
	v_ashrrev_i32_e32 v7, 5, v1
	s_add_i32 s3, s3, 0
	v_lshlrev_b32_e32 v2, 2, v4
	s_add_i32 s3, s3, 0x11400
	v_lshlrev_b32_e32 v188, 4, v7
	v_and_b32_e32 v0, 31, v1
	v_writelane_b32 v254, s4, 45
	v_ashrrev_i32_e32 v3, 31, v2
	v_add_u32_e32 v189, s3, v188
	s_lshl_b32 s3, s7, 5
	v_ashrrev_i32_e32 v184, 3, v4
	v_writelane_b32 v254, s5, 46
	v_lshl_add_u64 v[2:3], v[2:3], 2, s[0:1]
	s_mov_b64 s[4:5], 0x42c00000
	s_movk_i32 s11, 0x110
	v_or_b32_e32 v12, s3, v0
	v_lshlrev_b32_e32 v187, 2, v1
	v_lshl_add_u64 v[120:121], v[2:3], 0, s[4:5]
	v_mul_lo_u32 v2, v184, s11
	v_mad_u32_u24 v13, v12, s11, 0
	s_movk_i32 s4, 0xfef2
	v_add_u32_e32 v8, 0, v2
	v_and_b32_e32 v2, 16, v1
	v_and_b32_e32 v3, 12, v187
	v_mad_i32_i24 v190, v12, s4, v13
	s_add_u32 s4, s0, s6
	v_or3_b32 v17, v2, s9, v3
	v_or3_b32 v2, v2, s3, v3
	s_addc_u32 s5, s1, 0
	v_lshl_add_u32 v18, v2, 1, 0
	v_ashrrev_i32_e32 v19, 3, v1
	v_mov_b64_e32 v[2:3], s[4:5]
	v_mad_i64_i32 v[2:3], s[4:5], v19, s50, v[2:3]
	s_lshl_b32 s4, s7, 16
	s_add_u32 s0, s0, s4
	s_addc_u32 s1, s1, 0
	s_add_u32 s70, s0, 0x4b00000
	s_addc_u32 s71, s1, 0
	v_and_b32_e32 v5, 7, v1
	v_lshlrev_b32_e32 v11, 2, v7
	s_cmp_gt_i32 s2, 3
	v_add_u32_e32 v14, s9, v11
	v_lshlrev_b32_e32 v128, 4, v5
	s_cselect_b64 s[58:59], -1, 0
	s_sub_i32 s0, s9, 64
	v_lshlrev_b32_e32 v15, 4, v4
	v_lshlrev_b32_e32 v4, 3, v7
	v_bfe_u32 v7, v1, 2, 2
	v_lshl_add_u64 v[122:123], v[2:3], 0, v[128:129]
	v_cmp_eq_u32_e64 s[40:41], 0, v1
	v_or_b32_e32 v1, s0, v0
	v_add_u32_e32 v2, s0, v11
	v_cmp_ge_i32_e64 s[0:1], v12, v14
	v_or_b32_e32 v3, 1, v14
	s_movk_i32 s10, 0x90
	v_writelane_b32 v254, s0, 47
	v_mul_lo_u32 v20, v3, s10
	v_lshlrev_b32_e32 v185, 4, v5
	v_writelane_b32 v254, s1, 48
	v_cmp_le_i32_e64 s[0:1], v12, v14
	v_lshlrev_b32_e32 v186, 3, v5
	v_lshlrev_b32_e32 v9, 5, v5
	v_writelane_b32 v254, s0, 49
	v_mul_u32_u24_e32 v5, 0x110, v0
	v_or_b32_e32 v16, v4, v7
	v_writelane_b32 v254, s1, 50
	v_cmp_ge_i32_e64 s[0:1], v12, v3
	v_mul_lo_u32 v1, v1, s10
	v_mul_lo_u32 v192, v14, s10
	v_writelane_b32 v254, s0, 51
	v_add_u32_e32 v6, 0, v185
	v_mul_lo_u32 v10, v184, s10
	v_writelane_b32 v254, s1, 52
	v_cmp_le_i32_e64 s[0:1], v12, v3
	v_or_b32_e32 v3, 2, v14
	v_mul_lo_u32 v21, v3, s10
	v_writelane_b32 v254, s0, 53
	v_lshl_add_u32 v17, v17, 1, 0
	v_add_u32_e32 v191, 0, v1
	v_writelane_b32 v254, s1, 54
	v_cmp_ge_i32_e64 s[0:1], v12, v3
	v_lshlrev_b32_e32 v1, 1, v14
	v_mul_lo_u32 v19, v16, s11
	v_writelane_b32 v254, s0, 55
	v_mul_lo_u32 v16, v16, s10
	v_add_u32_e32 v23, 0x480, v192
	v_writelane_b32 v254, s1, 56
	v_cmp_le_i32_e64 s[0:1], v12, v3
	v_or_b32_e32 v3, 3, v14
	v_mul_lo_u32 v22, v3, s10
	v_writelane_b32 v254, s0, 57
	v_add_u32_e32 v24, 0x510, v192
	v_add_u32_e32 v25, 0x5a0, v192
	v_writelane_b32 v254, s1, 58
	v_cmp_ge_i32_e64 s[0:1], v12, v3
	v_lshlrev_b32_e32 v158, 1, v0
	v_add_u32_e32 v0, 0, v15
	v_writelane_b32 v254, s0, 59
	s_lshl_b32 s72, s3, 1
	v_add_u32_e32 v197, v8, v9
	v_writelane_b32 v254, s1, 60
	v_cmp_le_i32_e64 s[0:1], v12, v3
	v_add_u32_e32 v3, 8, v14
	v_add_u32_e32 v198, v6, v10
	v_writelane_b32 v254, s0, 61
	v_add_u32_e32 v199, 0x11400, v0
	v_add_u32_e32 v200, v13, v1
	v_writelane_b32 v254, s1, 62
	v_cmp_ge_i32_e64 s[0:1], v12, v3
; #define LAS __attribute__((address_space(3)))
; DI unsigned short f2bf1(float x) { return (unsigned short)(pk2(x, 0.f) & 0xffffu); }
; DI void phase_scan(int l, int wv, bool fill, bool last) {
;     ...
;             const bool outp = !(last && c < 4);
;             if (w < 4 && outp) {
;                 const int tb = w >> 1, sb = w & 1;
;                 f32x16 acc;
; #pragma unroll
;                 for (int i = 0; i < 16; ++i) acc[i] = 0.f;
; #pragma unroll 4
;                 for (int ks = 0; ks < 8; ++ks) { const bf16x8v a = *(const LAS bf16x8v*)(L + O_QT + (tb * 32 + r32) * RS + (ks * 16 + 8 * hh) * 2), bq = *(const LAS bf16x8v*)(L + O_KT + (sb * 32 + r32) * RS + (ks * 16 + 8 * hh) * 2);
;                     acc = __builtin_amdgcn_mfma_f32_32x32x16_bf16(a, bq, acc, 0, 0, 0); }
; #pragma unroll
;                 for (int i = 0; i < 16; ++i) { const int t = tb * 32 + (i & 3) + 8 * (i >> 2) + 4 * hh, sp = sb * 32 + r32; const bool keep = dir ? (sp >= t) : (sp <= t);
;                     *(LAS unsigned short*)(L + O_PM + t * RS64 + sp * 2) = f2bf1(keep ? acc[i] : 0.f); }
;     ...
;                 bf16* ob = (bf16*)F.OSC + ((size_t)dir * NTOK + row0) * DC + h * DK + vh * 64 + vb * 32 + r32;
; #pragma unroll
;                 for (int i = 0; i < 16; ++i) { const int t = tb * 32 + (i & 3) + 8 * (i >> 2) + 4 * hh; ob[(size_t)t * DC] = f2bf1(acc[i]); }
	v_add_u32_e32 v201, v17, v19
	v_add_u32_e32 v202, v190, v20
	v_writelane_b32 v254, s0, 63
	v_add_u32_e32 v203, v190, v21
	v_add_u32_e32 v204, v190, v22
	v_writelane_b32 v255, s1, 0
	v_cmp_le_i32_e64 s[0:1], v12, v3
	v_add_u32_e32 v3, 9, v14
	v_add_u32_e32 v205, v190, v23
	v_writelane_b32 v255, s0, 1
	v_add_u32_e32 v214, v190, v24
	v_add_u32_e32 v215, v190, v25
	v_writelane_b32 v255, s1, 2
	v_cmp_ge_i32_e64 s[0:1], v12, v3
	v_add_u32_e32 v231, v18, v16
	s_nop 0
	v_writelane_b32 v255, s0, 3
	s_nop 1
	v_writelane_b32 v255, s1, 4
	v_cmp_le_i32_e64 s[0:1], v12, v3
	v_add_u32_e32 v3, 10, v14
	s_nop 0
	v_writelane_b32 v255, s0, 5
	s_nop 1
	v_writelane_b32 v255, s1, 6
	v_cmp_ge_i32_e64 s[0:1], v12, v3
	s_nop 1
	v_writelane_b32 v255, s0, 7
	s_nop 1
	v_writelane_b32 v255, s1, 8
	v_cmp_le_i32_e64 s[0:1], v12, v3
	v_add_u32_e32 v3, 11, v14
	v_add_u32_e32 v14, 0x630, v192
	v_writelane_b32 v255, s0, 9
	v_add_u32_e32 v216, v190, v14
	s_nop 0
	v_writelane_b32 v255, s1, 10
	v_cmp_ge_i32_e64 s[0:1], v12, v3
	s_nop 1
	v_writelane_b32 v255, s0, 11
	s_nop 1
	v_writelane_b32 v255, s1, 12
	v_cmp_le_i32_e64 s[0:1], v12, v3
	s_nop 1
	v_writelane_b32 v255, s0, 13
	s_nop 1
	v_writelane_b32 v255, s1, 14
	s_or_b32 s0, s8, 16
	v_add_u32_e32 v3, s0, v11
	v_cmp_ge_i32_e64 s[0:1], v12, v3
	v_mul_lo_u32 v26, v3, s10
	v_add_u32_e32 v217, v190, v26
	v_writelane_b32 v255, s0, 15
	s_nop 1
	v_writelane_b32 v255, s1, 16
	v_cmp_le_i32_e64 s[0:1], v12, v3
	s_nop 1
	v_writelane_b32 v255, s0, 17
	s_nop 1
	v_writelane_b32 v255, s1, 18
	s_or_b32 s0, s8, 17
	v_add_u32_e32 v3, s0, v11
	v_cmp_ge_i32_e64 s[0:1], v12, v3
	v_mul_lo_u32 v27, v3, s10
	v_add_u32_e32 v218, v190, v27
	v_writelane_b32 v255, s0, 19
	s_nop 1
	v_writelane_b32 v255, s1, 20
	v_cmp_le_i32_e64 s[0:1], v12, v3
	s_nop 1
	v_writelane_b32 v255, s0, 21
	s_nop 1
	v_writelane_b32 v255, s1, 22
	s_or_b32 s0, s8, 18
	v_add_u32_e32 v3, s0, v11
	s_or_b32 s0, s8, 19
	v_add_u32_e32 v28, s0, v11
	s_or_b32 s0, s8, 24
	v_add_u32_e32 v29, s0, v11
	s_or_b32 s0, s8, 25
	v_add_u32_e32 v30, s0, v11
	s_or_b32 s0, s8, 26
	v_add_u32_e32 v31, s0, v11
	v_cmp_ge_i32_e64 s[0:1], v12, v3
	v_mul_lo_u32 v33, v3, s10
	v_mul_lo_u32 v34, v28, s10
	v_writelane_b32 v255, s0, 23
	v_mul_lo_u32 v35, v29, s10
	v_mul_lo_u32 v36, v30, s10
	v_writelane_b32 v255, s1, 24
	s_or_b32 s0, s8, 27
	v_add_u32_e32 v11, s0, v11
	s_lshr_b32 s0, s2, 1
	s_mulk_i32 s0, 0x2200
	v_add3_u32 v32, s0, v5, v188
	v_cmp_le_i32_e64 s[0:1], v12, v3
	v_add_u32_e32 v3, 16, v4
	v_lshlrev_b32_e32 v39, 1, v3
	v_or_b32_e32 v3, v3, v7
	v_mul_lo_u32 v40, v3, s10
	v_add_u32_e32 v3, 32, v4
	v_lshlrev_b32_e32 v41, 1, v3
	v_or_b32_e32 v3, v3, v7
	v_mul_lo_u32 v42, v3, s10
	v_add_u32_e32 v3, 48, v4
	v_or_b32_e32 v4, 1, v2
	v_ashrrev_i32_e32 v5, 31, v4
	v_lshlrev_b64 v[126:127], 11, v[4:5]
	v_or_b32_e32 v4, 2, v2
	v_ashrrev_i32_e32 v5, 31, v4
	v_lshlrev_b64 v[130:131], 11, v[4:5]
	v_or_b32_e32 v4, 3, v2
	v_ashrrev_i32_e32 v5, 31, v4
	v_lshlrev_b64 v[132:133], 11, v[4:5]
	v_add_u32_e32 v4, 8, v2
	v_ashrrev_i32_e32 v5, 31, v4
	v_lshlrev_b64 v[134:135], 11, v[4:5]
	v_add_u32_e32 v4, 9, v2
	v_ashrrev_i32_e32 v5, 31, v4
	v_lshlrev_b64 v[136:137], 11, v[4:5]
	v_add_u32_e32 v4, 10, v2
	v_ashrrev_i32_e32 v5, 31, v4
	v_lshlrev_b64 v[138:139], 11, v[4:5]
	v_add_u32_e32 v4, 11, v2
	v_ashrrev_i32_e32 v5, 31, v4
	v_lshlrev_b64 v[140:141], 11, v[4:5]
	v_add_u32_e32 v4, 16, v2
	v_ashrrev_i32_e32 v5, 31, v4
	v_lshlrev_b64 v[142:143], 11, v[4:5]
	v_add_u32_e32 v4, 17, v2
	v_ashrrev_i32_e32 v5, 31, v4
	v_lshlrev_b64 v[144:145], 11, v[4:5]
	v_add_u32_e32 v4, 18, v2
	v_ashrrev_i32_e32 v5, 31, v4
	v_lshlrev_b64 v[146:147], 11, v[4:5]
	v_add_u32_e32 v4, 19, v2
	v_ashrrev_i32_e32 v5, 31, v4
	v_lshlrev_b64 v[148:149], 11, v[4:5]
	v_add_u32_e32 v4, 24, v2
	v_ashrrev_i32_e32 v5, 31, v4
	v_lshlrev_b32_e32 v43, 1, v3
	v_or_b32_e32 v3, v3, v7
	v_lshlrev_b64 v[150:151], 11, v[4:5]
	v_add_u32_e32 v4, 25, v2
	v_mul_lo_u32 v7, v3, s10
	v_ashrrev_i32_e32 v3, 31, v2
	v_ashrrev_i32_e32 v5, 31, v4
	v_lshlrev_b64 v[124:125], 11, v[2:3]
	v_lshlrev_b64 v[152:153], 11, v[4:5]
	v_add_u32_e32 v4, 26, v2
	v_add_u32_e32 v2, 27, v2
	v_writelane_b32 v255, s0, 25
	v_ashrrev_i32_e32 v3, 31, v2
	v_lshlrev_b64 v[156:157], 11, v[2:3]
	v_writelane_b32 v255, s1, 26
	v_mad_u32_u24 v2, v12, s11, v188
	v_readlane_b32 s0, v254, 9
	v_mul_lo_u32 v37, v31, s10
	v_mul_lo_u32 v38, v11, s10
	v_add_u32_e32 v193, s0, v2
	v_readlane_b32 s0, v254, 10
	v_ashrrev_i32_e32 v5, 31, v4
	v_lshlrev_b64 v[154:155], 11, v[4:5]
	v_add_u32_e32 v195, s0, v2
	v_readlane_b32 s0, v254, 11
	v_add_u32_e32 v194, 0, v32
	v_add_u32_e32 v219, v190, v33
	v_add_u32_e32 v196, s0, v32
	v_readlane_b32 s0, v254, 19
	v_readlane_b32 s1, v254, 20
	v_add_u32_e32 v220, v190, v34
	v_add_u32_e32 v221, v190, v35
	v_add_u32_e32 v222, v190, v36
	v_add_u32_e32 v223, v190, v37
	v_add_u32_e32 v224, v190, v38
	v_add_u32_e32 v225, v191, v39
	v_add_u32_e32 v226, v18, v40
	v_add_u32_e32 v227, v191, v41
	v_add_u32_e32 v228, v18, v42
	v_add_u32_e32 v229, v191, v43
	v_add_u32_e32 v230, v18, v7
	s_mov_b32 s73, s0
	v_cmp_ge_i32_e64 s[86:87], v12, v28
	v_cmp_le_i32_e64 s[88:89], v12, v28
	v_cmp_ge_i32_e64 s[90:91], v12, v29
	v_cmp_le_i32_e64 s[92:93], v12, v29
	v_cmp_ge_i32_e64 s[94:95], v12, v30
	v_cmp_le_i32_e64 s[96:97], v12, v30
	v_cmp_ge_i32_e64 s[0:1], v12, v31
	v_cmp_le_i32_e64 s[4:5], v12, v31
	v_cmp_ge_i32_e64 s[6:7], v12, v11
	v_cmp_le_i32_e64 s[8:9], v12, v11
	s_branch .LBB0_474

; DI void phase_scan(int l, int wv, bool fill, bool last) {
;     ...
;             if (filler && c < 32) {
;                 const int it = fidx + 1024 * c, e = it >> 1; unsigned char* dst = (it & 1) ? (unsigned char*)F.V : (unsigned char*)F.U;
;                 float am = 0.f;
; #pragma unroll
;                 for (int c8 = 0; c8 < 8; ++c8) am = fmaxf(am, fmaxf(fmaxf(fabsf(fx[c8].x), fabsf(fx[c8].y)), fmaxf(fabsf(fx[c8].z), fabsf(fx[c8].w))));
; #pragma unroll
;                 for (int o = 1; o < 64; o <<= 1) am = fmaxf(am, __shfl_xor(am, o));
;                 const float inv = am > 0.f ? 7.0f / am : 0.f, sc = am > 0.f ? am * (1.0f / 7.0f) : 0.f;
;                 v32h hx;
; #pragma unroll
;                 for (int c8 = 0; c8 < 8; ++c8) { hx[c8 * 4 + 0] = (_Float16)(fx[c8].x * inv); hx[c8 * 4 + 1] = (_Float16)(fx[c8].y * inv); hx[c8 * 4 + 2] = (_Float16)(fx[c8].z * inv); hx[c8 * 4 + 3] = (_Float16)(fx[c8].w * inv); }
;                 const v6i p = __builtin_amdgcn_cvt_scalef32_pk32_fp6_f16(hx, 1.0f);
;                 eseg_store(dst, e, lane, p);
;                 if (lane == 0) ((float*)(F.ws + WS_ESCALE) + ((it & 1) ? NEXP : 0))[e] = sc;
.LBB0_498:
	s_cmp_lt_u32 s78, 32
	s_cselect_b64 s[62:63], -1, 0
	s_and_b64 s[62:63], s[56:57], s[62:63]
	s_andn2_b64 vcc, exec, s[62:63]
	s_waitcnt lgkmcnt(0)
	s_barrier
	s_cbranch_vccnz .LBB0_503
	v_max_f32_e64 v16, |v35|, |v35|
	v_max_f32_e64 v17, |v34|, |v34|
	v_max_f32_e32 v16, v17, v16
	v_max_f32_e64 v17, |v43|, |v43|
	v_max_f32_e64 v18, |v42|, |v42|
	v_max_f32_e32 v17, v18, v17
	v_max3_f32 v16, |v32|, |v33|, v16
	v_max3_f32 v17, |v40|, |v41|, v17
	v_max3_f32 v16, v16, 0, v17
	v_max_f32_e64 v17, |v55|, |v55|
	v_max_f32_e64 v18, |v54|, |v54|
	v_max_f32_e32 v17, v18, v17
	v_max_f32_e64 v18, |v63|, |v63|
	v_max_f32_e64 v19, |v62|, |v62|
	v_max_f32_e32 v18, v19, v18
	v_max3_f32 v17, |v52|, |v53|, v17
	v_max3_f32 v18, |v60|, |v61|, v18
	v_max3_f32 v16, v16, v17, v18
	v_max_f32_e64 v17, |v51|, |v51|
	v_max_f32_e64 v18, |v50|, |v50|
	v_max_f32_e32 v17, v18, v17
	v_max_f32_e64 v18, |v39|, |v39|
	v_max_f32_e64 v19, |v38|, |v38|
	v_max_f32_e32 v18, v19, v18
	v_max3_f32 v17, |v48|, |v49|, v17
	v_max3_f32 v18, |v36|, |v37|, v18
	v_max3_f32 v16, v16, v17, v18
	v_max_f32_e64 v17, |v47|, |v47|
	v_max_f32_e64 v18, |v46|, |v46|
	v_max_f32_e32 v17, v18, v17
	v_max_f32_e64 v18, |v59|, |v59|
	v_max_f32_e64 v19, |v58|, |v58|
	v_max_f32_e32 v18, v19, v18
	v_max3_f32 v17, |v44|, |v45|, v17
	v_max3_f32 v18, |v56|, |v57|, v18
	v_max3_f32 v16, v16, v17, v18
	v_and_b32_e32 v17, 64, v239
	v_add_u32_e32 v17, 64, v17
	v_xor_b32_e32 v18, 1, v239
	v_cmp_lt_i32_e32 vcc, v18, v17
	s_mov_b32 s64, 0x40e00000
	s_lshl_b32 s81, s78, 10
	v_cndmask_b32_e32 v18, v239, v18, vcc
	v_lshlrev_b32_e32 v18, 2, v18
	ds_bpermute_b32 v18, v18, v16
	s_add_i32 s81, s81, s67
	s_waitcnt lgkmcnt(0)
	v_max_f32_e32 v18, v18, v18
	v_max_f32_e32 v16, v16, v18
	v_xor_b32_e32 v18, 2, v239
	v_cmp_lt_i32_e32 vcc, v18, v17
	s_nop 1
	v_cndmask_b32_e32 v18, v239, v18, vcc
	v_lshlrev_b32_e32 v18, 2, v18
	ds_bpermute_b32 v18, v18, v16
	s_waitcnt lgkmcnt(0)
	v_max_f32_e32 v18, v18, v18
	v_max_f32_e32 v16, v16, v18
	v_xor_b32_e32 v18, 4, v239
	v_cmp_lt_i32_e32 vcc, v18, v17
	s_nop 1
	v_cndmask_b32_e32 v18, v239, v18, vcc
	v_lshlrev_b32_e32 v18, 2, v18
	ds_bpermute_b32 v18, v18, v16
	s_waitcnt lgkmcnt(0)
	v_max_f32_e32 v18, v18, v18
	v_max_f32_e32 v16, v16, v18
	v_xor_b32_e32 v18, 8, v239
	v_cmp_lt_i32_e32 vcc, v18, v17
	s_nop 1
	v_cndmask_b32_e32 v18, v239, v18, vcc
	v_lshlrev_b32_e32 v18, 2, v18
	ds_bpermute_b32 v18, v18, v16
	s_waitcnt lgkmcnt(0)
	v_max_f32_e32 v18, v18, v18
	v_max_f32_e32 v16, v16, v18
	v_xor_b32_e32 v18, 16, v239
	v_cmp_lt_i32_e32 vcc, v18, v17
	s_nop 1
	v_cndmask_b32_e32 v18, v239, v18, vcc
	v_lshlrev_b32_e32 v18, 2, v18
	ds_bpermute_b32 v18, v18, v16
	s_waitcnt lgkmcnt(0)
	v_max_f32_e32 v18, v18, v18
	v_max_f32_e32 v16, v16, v18
	v_xor_b32_e32 v18, 32, v239
	v_cmp_lt_i32_e32 vcc, v18, v17
	s_nop 1
	v_cndmask_b32_e32 v17, v239, v18, vcc
	v_lshlrev_b32_e32 v17, 2, v17
	ds_bpermute_b32 v17, v17, v16
	s_waitcnt lgkmcnt(0)
	v_max_f32_e32 v17, v17, v17
	v_max_f32_e32 v159, v16, v17
	v_div_scale_f32 v16, s[62:63], v159, v159, s64
	v_rcp_f32_e32 v17, v16
	s_ashr_i32 s62, s81, 1
	v_fma_f32 v18, -v16, v17, 1.0
	v_fmac_f32_e32 v17, v18, v17
	v_div_scale_f32 v18, vcc, s64, v159, s64
	v_mul_f32_e32 v19, v18, v17
	v_fma_f32 v20, -v16, v19, v18
	v_fmac_f32_e32 v19, v20, v17
	v_fma_f32 v16, -v16, v19, v18
	v_div_fmas_f32 v16, v16, v17, v19
	v_div_fixup_f32 v16, v16, v159, s64
	v_cmp_lt_f32_e32 vcc, 0, v159
	v_mov_b32_e32 v17, v34
	s_nop 0
	v_cndmask_b32_e32 v208, 0, v16, vcc
	v_mov_b32_e32 v16, v33
	v_pk_mul_f32 v[16:17], v[16:17], v[208:209] op_sel_hi:[1,0]
	v_fma_mixlo_f16 v18, v32, v208, 0
	v_cvt_pk_f16_f32 v17, v16, v17
	v_pack_b32_f16 v16, v18, v17
	v_pk_mov_b32 v[18:19], v[34:35], v[40:41] op_sel:[1,0]
	s_nop 0
	v_pk_mul_f32 v[18:19], v[18:19], v[208:209] op_sel_hi:[1,0]
	s_nop 0
	v_cvt_pk_f16_f32 v20, v18, v19
	v_mov_b32_e32 v18, v41
	v_mov_b32_e32 v19, v42
	v_pk_mul_f32 v[18:19], v[18:19], v[208:209] op_sel_hi:[1,0]
	v_alignbit_b32 v17, v20, v17, 16
	v_cvt_pk_f16_f32 v19, v18, v19
	v_alignbit_b32 v18, v19, v20, 16
	v_pk_mov_b32 v[20:21], v[42:43], v[52:53] op_sel:[1,0]
	s_nop 0
	v_pk_mul_f32 v[20:21], v[20:21], v[208:209] op_sel_hi:[1,0]
	s_nop 0
	v_cvt_pk_f16_f32 v22, v20, v21
	v_mov_b32_e32 v20, v53
	v_mov_b32_e32 v21, v54
	v_pk_mul_f32 v[20:21], v[20:21], v[208:209] op_sel_hi:[1,0]
	v_alignbit_b32 v19, v22, v19, 16
	v_cvt_pk_f16_f32 v21, v20, v21
	v_alignbit_b32 v20, v21, v22, 16
	v_pk_mov_b32 v[22:23], v[54:55], v[60:61] op_sel:[1,0]
	s_nop 0
	v_pk_mul_f32 v[22:23], v[22:23], v[208:209] op_sel_hi:[1,0]
	s_nop 0
	v_cvt_pk_f16_f32 v24, v22, v23
	v_mov_b32_e32 v22, v61
	v_mov_b32_e32 v23, v62
	v_pk_mul_f32 v[22:23], v[22:23], v[208:209] op_sel_hi:[1,0]
	v_alignbit_b32 v21, v24, v21, 16
	v_cvt_pk_f16_f32 v23, v22, v23
	v_alignbit_b32 v22, v23, v24, 16
	v_pk_mov_b32 v[24:25], v[62:63], v[48:49] op_sel:[1,0]
	s_nop 0
	v_pk_mul_f32 v[24:25], v[24:25], v[208:209] op_sel_hi:[1,0]
	s_nop 0
	v_cvt_pk_f16_f32 v26, v24, v25
	v_mov_b32_e32 v24, v49
	v_mov_b32_e32 v25, v50
	v_pk_mul_f32 v[24:25], v[24:25], v[208:209] op_sel_hi:[1,0]
	v_alignbit_b32 v23, v26, v23, 16
	v_cvt_pk_f16_f32 v25, v24, v25
	v_alignbit_b32 v24, v25, v26, 16
	v_pk_mov_b32 v[26:27], v[50:51], v[36:37] op_sel:[1,0]
	s_nop 0
	v_pk_mul_f32 v[26:27], v[26:27], v[208:209] op_sel_hi:[1,0]
	s_nop 0
	v_cvt_pk_f16_f32 v28, v26, v27
	v_mov_b32_e32 v26, v37
	v_mov_b32_e32 v27, v38
	v_pk_mul_f32 v[26:27], v[26:27], v[208:209] op_sel_hi:[1,0]
	v_alignbit_b32 v25, v28, v25, 16
	v_cvt_pk_f16_f32 v27, v26, v27
	v_alignbit_b32 v26, v27, v28, 16
	v_pk_mov_b32 v[28:29], v[38:39], v[44:45] op_sel:[1,0]
	s_nop 0
	v_pk_mul_f32 v[28:29], v[28:29], v[208:209] op_sel_hi:[1,0]
	s_nop 0
	v_cvt_pk_f16_f32 v30, v28, v29
	v_mov_b32_e32 v28, v45
	v_mov_b32_e32 v29, v46
	v_pk_mul_f32 v[28:29], v[28:29], v[208:209] op_sel_hi:[1,0]
	v_alignbit_b32 v27, v30, v27, 16
	v_cvt_pk_f16_f32 v29, v28, v29
	v_alignbit_b32 v28, v29, v30, 16
	v_pk_mov_b32 v[30:31], v[46:47], v[56:57] op_sel:[1,0]
	s_nop 0
	v_pk_mul_f32 v[30:31], v[30:31], v[208:209] op_sel_hi:[1,0]
	s_nop 0
	v_cvt_pk_f16_f32 v161, v30, v31
	v_mov_b32_e32 v30, v57
	v_mov_b32_e32 v31, v58
	v_pk_mul_f32 v[30:31], v[30:31], v[208:209] op_sel_hi:[1,0]
	v_alignbit_b32 v29, v161, v29, 16
	v_cvt_pk_f16_f32 v31, v30, v31
	v_alignbit_b32 v30, v31, v161, 16
	v_lshrrev_b32_e32 v31, 16, v31
	v_fma_mixhi_f16 v31, v59, v208, 0
	v_cvt_scalef32_pk32_fp6_f16 v[232:237], v[16:31], 1.0
	s_lshl_b32 s64, s62, 7
	s_mov_b32 s65, 0
	v_lshl_add_u64 v[16:17], v[122:123], 0, s[64:65]
	global_store_dwordx4 v[16:17], v[232:235], off
	v_and_b32_e32 v18, 7, v239
	s_lshl_b32 s64, s62, 6
	v_lshlrev_b32_e32 v18, 3, v18
	s_sub_u32 s64, 0x200000, s64
	v_mov_b32_e32 v19, 0
	v_sub_u32_e32 v18, s64, v18
	v_lshl_add_u64 v[18:19], v[16:17], 0, v[18:19]
	global_store_dwordx2 v[18:19], v[236:237], off
	s_and_saveexec_b64 s[64:65], s[40:41]
	s_cbranch_execz .LBB0_501
; DI void phase_scan(int l, int wv, bool fill, bool last) {
;     ...
;                 if (lane == 0) ((float*)(F.ws + WS_ESCALE) + ((it & 1) ? NEXP : 0))[e] = sc;
	s_ashr_i32 s63, s62, 31
	s_lshl_b64 s[62:63], s[62:63], 2
	s_add_u32 s62, s70, s62
	v_mul_f32_e32 v16, 0x3e124925, v159
	s_addc_u32 s63, s71, s63
	v_cndmask_b32_e32 v16, 0, v16, vcc
	global_store_dword v129, v16, s[62:63]

; DI void eseg_load(ESeg& r, __amdgpu_buffer_rsrc_t rs, int voff) { r.a = __builtin_amdgcn_raw_buffer_load_b128(rs, voff, 0, 0); r.b = __builtin_amdgcn_raw_buffer_load_b64(rs, voff + 16, 0, 0); }
; DI int id_of(const u32x4 (&d)[2], int r, unsigned mask = 0xffffu) { const unsigned w = d[r >> 3][(r >> 1) & 3]; return (r & 1) ? (int)((w >> 16) & mask) : (int)(w & mask); }
;     const Frame F = mkframe(wv);
;     int x, wx, nwx; xcd_split(F, x, wx, nwx);
;     const int lane = F.lane, s = lane & 7, g = lane >> 3, s24 = s * 24;
;     const __amdgpu_buffer_rsrc_t US = __builtin_amdgcn_make_buffer_rsrc((void*)uniform_ptr((unsigned char*)F.U + (size_t)x * ESLICE), 0, (int)ESLICE, 0x00020000);
;     const unsigned short* RI16 = (const unsigned short*)(F.ws + WS_RIDX);
;     float* P = (float*)(F.ws + WS_PP) + (size_t)x * NTOK * 128;
;     const bf16* Hs = F.H + (8 * x + s) * 4;
;     int t = wx; if (t >= nrows) return;
;     ESeg rw[16]; u32x4 idn[2], idnn[2]; u32x2 hp[8];
;     { u32x4 idc[2]; ids_load(idc, RI16, t, g);
; #pragma unroll
;       for (int r = 0; r < 16; ++r) eseg_load(rw[r], US, id_of(idc, r, mask) * ESEG + s24); }
; #pragma unroll
;     for (int c = 0; c < 8; ++c) hp[c] = *(const u32x2*)(Hs + (size_t)t * D + c * 256);
;     ids_load(idn, RI16, t + nwx < nrows ? t + nwx : t, g);
;     __builtin_amdgcn_s_waitcnt(0);
.LBB0_976:
	s_andn2_b64 vcc, exec, s[0:1]
	s_cbranch_vccnz .LBB0_1032
	s_waitcnt vmcnt(0)
	v_mov_b32_e32 v0, v129
	s_mov_b32 s0, s88
	v_mbcnt_lo_u32_b32 v0, -1, v0
	v_mbcnt_hi_u32_b32 v0, -1, v0
	s_load_dword s4, s[90:91], 0x0
	v_readlane_b32 s1, v253, 54
	v_readlane_b32 s3, v252, 0
	v_readlane_b32 s2, v253, 33
	v_mov_b32_e32 v1, s1
	ds_read_b64 v[2:3], v1
	v_mov_b32_e32 v1, s79
	s_waitcnt lgkmcnt(0)
	ds_read_b64 v[2:3], v1
	s_add_i32 s3, s0, s3
	s_and_b32 s1, s4, 7
	s_add_i32 s2, s0, s2
	s_ashr_i32 s3, s3, 3
	s_cmp_eq_u32 s1, 0
	s_cselect_b32 s0, s80, s0
	s_cselect_b32 s10, s2, s3
	s_and_b32 s2, s0, 7
	s_waitcnt lgkmcnt(0)
	v_readfirstlane_b32 s6, v2
	s_mul_i32 s0, s2, 0x300000
	v_readfirstlane_b32 s7, v3
	s_add_u32 s0, s6, s0
	s_addc_u32 s1, s7, 0
	s_add_u32 s48, s0, 0x4c00000
	s_addc_u32 s0, s1, 0
	s_cmp_ge_i32 s10, s15
	s_movk_i32 s14, 0xc0
	s_cbranch_scc1 .LBB0_980
	s_and_b32 s49, s0, 0xffff
	s_add_u32 s0, s6, 0x42c00000
	s_addc_u32 s1, s7, 0
	s_ashr_i32 s11, s10, 31
	v_lshlrev_b32_e32 v1, 1, v0
	s_lshl_b64 s[8:9], s[10:11], 8
	v_and_b32_e32 v10, -16, v1
	s_add_u32 s8, s0, s8
	v_ashrrev_i32_e32 v11, 31, v10
	s_addc_u32 s9, s1, s9
	v_lshlrev_b64 v[12:13], 1, v[10:11]
	v_lshl_add_u64 v[6:7], s[8:9], 0, v[12:13]
	global_load_dwordx4 v[2:5], v[6:7], off
	s_nop 0
	global_load_dwordx4 v[6:9], v[6:7], off offset:16
	v_and_b32_e32 v14, 7, v0
	v_lshlrev_b32_e32 v15, 3, v14
	v_lshl_or_b32 v128, s2, 6, v15
	v_lshl_add_u64 v[0:1], s[6:7], 0, v[128:129]
	s_mov_b64 s[8:9], 0x15c00000
	v_lshlrev_b32_e32 v194, 4, v14
	v_lshlrev_b32_e32 v199, 3, v14
	v_add_u32_e32 v199, 0x200000, v199
	v_lshl_add_u64 v[130:131], v[0:1], 0, s[8:9]
	s_lshl_b64 s[8:9], s[10:11], 12
	v_lshl_add_u64 v[0:1], v[130:131], 0, s[8:9]
	global_load_dwordx2 v[158:159], v[0:1], off
	global_load_dwordx2 v[156:157], v[0:1], off offset:512
	global_load_dwordx2 v[154:155], v[0:1], off offset:1024
	global_load_dwordx2 v[152:153], v[0:1], off offset:1536
	s_add_i32 s3, s10, s4
	s_cmp_lt_i32 s3, s15
	s_cselect_b32 s8, s3, s10
	s_ashr_i32 s9, s8, 31
	s_lshl_b64 s[8:9], s[8:9], 8
	s_add_u32 s8, s0, s8
	s_addc_u32 s9, s1, s9
	s_mul_i32 s5, s2, 0x900000
	v_lshl_add_u64 v[132:133], s[0:1], 0, v[12:13]
	v_cmp_eq_u32_e64 s[36:37], 0, v14
	v_cmp_eq_u32_e64 s[38:39], 1, v14
	v_cmp_eq_u32_e64 s[40:41], 2, v14
	v_cmp_eq_u32_e64 s[42:43], 3, v14
	v_cmp_eq_u32_e64 s[44:45], 4, v14
	v_cmp_eq_u32_e64 s[46:47], 5, v14
	v_cmp_eq_u32_e64 s[0:1], 6, v14
	v_cmp_eq_u32_e64 s[2:3], 7, v14
	s_waitcnt vmcnt(5)
	v_and_b32_e32 v16, 0xffff, v2
	v_and_b32_e32 v17, 0xffff, v3
	v_and_b32_e32 v18, 0xffff, v4
	v_and_b32_e32 v19, 0xffff, v5
	s_waitcnt vmcnt(4)
	v_and_b32_e32 v20, 0xffff, v6
	v_and_b32_e32 v21, 0xffff, v7
	v_and_b32_e32 v22, 0xffff, v8
	v_and_b32_e32 v23, 0xffff, v9
	v_lshrrev_b32_e32 v2, 16, v2
	v_lshrrev_b32_e32 v3, 16, v3
	v_lshrrev_b32_e32 v4, 16, v4
	v_lshrrev_b32_e32 v5, 16, v5
	v_lshrrev_b32_e32 v6, 16, v6
	v_lshrrev_b32_e32 v7, 16, v7
	v_lshrrev_b32_e32 v8, 16, v8
	v_lshrrev_b32_e32 v9, 16, v9
	v_lshl_add_u32 v214, v16, 6, v199
	v_lshl_add_u32 v24, v16, 7, v194
	v_lshl_add_u32 v215, v17, 6, v199
	v_lshl_add_u32 v26, v17, 7, v194
	v_lshl_add_u32 v216, v18, 6, v199
	v_lshl_add_u32 v32, v18, 7, v194
	v_lshl_add_u32 v217, v19, 6, v199
	v_lshl_add_u32 v38, v19, 7, v194
	v_lshl_add_u32 v218, v20, 6, v199
	v_lshl_add_u32 v44, v20, 7, v194
	v_lshl_add_u32 v219, v21, 6, v199
	v_lshl_add_u32 v52, v21, 7, v194
	v_lshl_add_u32 v220, v22, 6, v199
	v_lshl_add_u32 v53, v22, 7, v194
	v_lshl_add_u32 v221, v23, 6, v199
	v_lshl_add_u32 v56, v23, 7, v194
	v_lshl_add_u32 v222, v2, 6, v199
	v_lshl_add_u32 v2, v2, 7, v194
	v_lshl_add_u32 v223, v3, 6, v199
	v_lshl_add_u32 v3, v3, 7, v194
	v_lshl_add_u32 v224, v4, 6, v199
	v_lshl_add_u32 v4, v4, 7, v194
	v_lshl_add_u32 v225, v5, 6, v199
	v_lshl_add_u32 v5, v5, 7, v194
	v_lshl_add_u32 v226, v6, 6, v199
	v_lshl_add_u32 v6, v6, 7, v194
	v_lshl_add_u32 v227, v7, 6, v199
	v_lshl_add_u32 v7, v7, 7, v194
	v_lshl_add_u32 v228, v8, 6, v199
	v_lshl_add_u32 v8, v8, 7, v194
	v_lshl_add_u32 v229, v9, 6, v199
	v_lshl_add_u32 v9, v9, 7, v194
	buffer_load_dwordx4 v[16:19], v24, s[48:51], 0 offen
	buffer_load_dwordx2 v[20:21], v214, s[48:51], 0 offen
	buffer_load_dwordx4 v[94:97], v2, s[48:51], 0 offen
	buffer_load_dwordx2 v[98:99], v222, s[48:51], 0 offen
	s_nop 0
	buffer_load_dwordx4 v[22:25], v26, s[48:51], 0 offen
	s_nop 0
	buffer_load_dwordx2 v[26:27], v215, s[48:51], 0 offen
	s_nop 0
	buffer_load_dwordx4 v[46:49], v3, s[48:51], 0 offen
	buffer_load_dwordx2 v[50:51], v223, s[48:51], 0 offen
	buffer_load_dwordx4 v[28:31], v32, s[48:51], 0 offen
	s_nop 0
	buffer_load_dwordx2 v[32:33], v216, s[48:51], 0 offen
	s_nop 0
	buffer_load_dwordx4 v[64:67], v4, s[48:51], 0 offen
	buffer_load_dwordx2 v[68:69], v224, s[48:51], 0 offen
	buffer_load_dwordx4 v[34:37], v38, s[48:51], 0 offen
	s_nop 0
	buffer_load_dwordx2 v[38:39], v217, s[48:51], 0 offen
	s_nop 0
	buffer_load_dwordx4 v[76:79], v5, s[48:51], 0 offen
	buffer_load_dwordx2 v[80:81], v225, s[48:51], 0 offen
	buffer_load_dwordx4 v[40:43], v44, s[48:51], 0 offen
	s_nop 0
	buffer_load_dwordx2 v[44:45], v218, s[48:51], 0 offen
	s_nop 0
	buffer_load_dwordx4 v[82:85], v6, s[48:51], 0 offen
	buffer_load_dwordx2 v[86:87], v226, s[48:51], 0 offen
	buffer_load_dwordx4 v[58:61], v52, s[48:51], 0 offen
	buffer_load_dwordx2 v[62:63], v219, s[48:51], 0 offen
	buffer_load_dwordx4 v[88:91], v7, s[48:51], 0 offen
	buffer_load_dwordx2 v[92:93], v227, s[48:51], 0 offen
	buffer_load_dwordx4 v[70:73], v53, s[48:51], 0 offen
	buffer_load_dwordx2 v[74:75], v220, s[48:51], 0 offen
	buffer_load_dwordx4 v[100:103], v8, s[48:51], 0 offen
	buffer_load_dwordx2 v[104:105], v228, s[48:51], 0 offen
	s_nop 0
	buffer_load_dwordx4 v[52:55], v56, s[48:51], 0 offen
	s_nop 0
	buffer_load_dwordx2 v[56:57], v221, s[48:51], 0 offen
	s_nop 0
	buffer_load_dwordx4 v[106:109], v9, s[48:51], 0 offen
	buffer_load_dwordx2 v[110:111], v229, s[48:51], 0 offen
	global_load_dwordx2 v[166:167], v[0:1], off offset:2048
	global_load_dwordx2 v[164:165], v[0:1], off offset:2560
	global_load_dwordx2 v[162:163], v[0:1], off offset:3072
	global_load_dwordx2 v[160:161], v[0:1], off offset:3584
	v_lshl_add_u64 v[0:1], s[8:9], 0, v[12:13]
	global_load_dwordx4 v[120:123], v[0:1], off offset:16
	global_load_dwordx4 v[124:127], v[0:1], off
	s_lshl_b64 s[8:9], s[10:11], 9
	s_add_u32 s5, s5, s8
	s_addc_u32 s8, 0, s9
	v_or_b32_e32 v0, s5, v15
	v_mov_b32_e32 v1, s8
	v_lshl_add_u64 v[0:1], v[10:11], 2, v[0:1]
	v_lshl_add_u64 v[0:1], s[6:7], 0, v[0:1]
	s_mov_b64 s[6:7], 0x39c00000
	s_ashr_i32 s5, s4, 31
	v_lshl_add_u64 v[134:135], v[0:1], 0, s[6:7]
	s_lshl_b64 s[6:7], s[4:5], 9
	s_lshl_b32 s5, s4, 1
	s_waitcnt vmcnt(0) expcnt(0) lgkmcnt(0)
; template <int CTRL> DI float dpp_add(float x) { return x + __uint_as_float(__builtin_amdgcn_update_dpp(0u, __float_as_uint(x), CTRL, 0xf, 0xf, true)); }
; DI int id_of(const u32x4 (&d)[2], int r, unsigned mask = 0xffffu) { const unsigned w = d[r >> 3][(r >> 1) & 3]; return (r & 1) ? (int)((w >> 16) & mask) : (int)(w & mask); }
; DI void eseg_load(ESeg& r, __amdgpu_buffer_rsrc_t rs, int voff) { r.a = __builtin_amdgcn_raw_buffer_load_b128(rs, voff, 0, 0); r.b = __builtin_amdgcn_raw_buffer_load_b64(rs, voff + 16, 0, 0); }
;     ...
;         const int tn = t + nwx, tnn = tn + nwx, tn_c = tn < nrows ? tn : t, tnn_c = tnn < nrows ? tnn : t;
;         ids_load(idnn, RI16, tnn_c, g);
;         u32x2 hq[8];
; #pragma unroll
;         for (int c = 0; c < 8; ++c) hq[c] = hp[c];
;         __builtin_amdgcn_sched_barrier(0);
; #pragma unroll
;         for (int c = 0; c < 8; ++c) hp[c] = *(const u32x2*)(Hs + (size_t)tn_c * D + c * 256);
;         __builtin_amdgcn_sched_barrier(0);
;         float o0 = 0.f, o1 = 0.f;
; #pragma unroll
;         for (int r = 0; r < 16; ++r) {
;             if (MODE == 2) { o0 += __uint_as_float(rw[r].a.x ^ rw[r].a.w ^ rw[r].b.y); eseg_load(rw[r], US, id_of(idn, r, mask) * ESEG + s24); if (r & 1) __builtin_amdgcn_sched_barrier(0); continue; }
;             typedef __bf16 bfx2 __attribute__((ext_vector_type(2))); typedef __bf16 bfx32 __attribute__((ext_vector_type(32)));
;             const bfx32 rr = __builtin_amdgcn_cvt_scalef32_pk32_bf16_fp6((v6i){(int)rw[r].a.x, (int)rw[r].a.y, (int)rw[r].a.z, (int)rw[r].a.w, (int)rw[r].b.x, (int)rw[r].b.y}, 1.0f);
;             float dA = 0.f, dB = 0.f;
;     ...
;             DOT2(0, dA); DOT2(1, dB); DOT2(2, dA); DOT2(3, dB); DOT2(4, dA); DOT2(5, dB); DOT2(6, dA); DOT2(7, dB); DOT2(8, dA); DOT2(9, dB); DOT2(10, dA); DOT2(11, dB); DOT2(12, dA); DOT2(13, dB); DOT2(14, dA); DOT2(15, dB);
;     ...
;             float d = dA + dB;
;             d = dpp_add<0xB1>(d); d = dpp_add<0x4E>(d); d = dpp_add<0x141>(d);
;             if ((r >> 1) == s) { if (r & 1) o1 = d; else o0 = d; }
;             if (MODE != 1) eseg_load(rw[r], US, id_of(idn, r, mask) * ESEG + s24);
;             else asm volatile("" : "+v"(rw[r].a.x), "+v"(rw[r].a.y), "+v"(rw[r].a.z), "+v"(rw[r].a.w), "+v"(rw[r].b.x), "+v"(rw[r].b.y));
;             if (r & 1) __builtin_amdgcn_sched_barrier(0);
.LBB0_979:
	s_add_i32 s11, s10, s4
	s_add_i32 s8, s5, s10
	s_cmp_lt_i32 s8, s15
	s_cselect_b32 s8, s8, s10
	s_ashr_i32 s9, s8, 31
	s_lshl_b64 s[8:9], s[8:9], 8
	v_lshl_add_u64 v[0:1], v[132:133], 0, s[8:9]
	global_load_dwordx4 v[112:115], v[0:1], off offset:16
	global_load_dwordx4 v[116:119], v[0:1], off
	s_cmp_lt_i32 s11, s15
	s_cselect_b64 s[8:9], -1, 0
	s_and_b64 s[12:13], s[8:9], exec
	s_cselect_b32 s12, s11, s10
	s_ashr_i32 s13, s12, 31
	s_lshl_b64 s[12:13], s[12:13], 12
	v_lshl_add_u64 v[0:1], v[130:131], 0, s[12:13]
	global_load_dwordx2 v[136:137], v[0:1], off
	global_load_dwordx2 v[138:139], v[0:1], off offset:512
	global_load_dwordx2 v[140:141], v[0:1], off offset:1024
	global_load_dwordx2 v[142:143], v[0:1], off offset:1536
	global_load_dwordx2 v[144:145], v[0:1], off offset:2048
	global_load_dwordx2 v[146:147], v[0:1], off offset:2560
	global_load_dwordx2 v[148:149], v[0:1], off offset:3072
	global_load_dwordx2 v[150:151], v[0:1], off offset:3584
	s_waitcnt vmcnt(41)
	v_cvt_scalef32_pk32_bf16_fp6 v[0:15], v[16:21], 1.0
	v_and_b32_e32 v195, 0xffff, v124
	v_lshl_add_u32 v198, v195, 6, v199
	v_lshl_add_u32 v195, v195, 7, v194
	buffer_load_dwordx4 v[16:19], v195, s[48:51], 0 offen
	buffer_load_dwordx2 v[20:21], v198, s[48:51], 0 offen
	v_dot2_f32_bf16 v168, v0, v158, 0
	v_dot2_f32_bf16 v170, v1, v159, 0
	v_dot2_f32_bf16 v168, v2, v156, v168
	v_dot2_f32_bf16 v170, v3, v157, v170
	v_dot2_f32_bf16 v168, v4, v154, v168
	v_dot2_f32_bf16 v170, v5, v155, v170
	v_dot2_f32_bf16 v168, v6, v152, v168
	v_dot2_f32_bf16 v170, v7, v153, v170
	v_dot2_f32_bf16 v168, v8, v166, v168
	v_dot2_f32_bf16 v170, v9, v167, v170
	v_dot2_f32_bf16 v168, v10, v164, v168
	v_dot2_f32_bf16 v170, v11, v165, v170
	v_dot2_f32_bf16 v168, v12, v162, v168
	v_dot2_f32_bf16 v170, v13, v163, v170
	v_dot2_f32_bf16 v168, v14, v160, v168
	v_dot2_f32_bf16 v170, v15, v161, v170
	s_waitcnt vmcnt(41)
	v_cvt_scalef32_pk32_bf16_fp6 v[0:15], v[94:99], 1.0
	v_lshrrev_b32_e32 v195, 16, v124
	v_lshl_add_u32 v198, v195, 6, v199
	v_lshl_add_u32 v195, v195, 7, v194
	buffer_load_dwordx4 v[94:97], v195, s[48:51], 0 offen
	buffer_load_dwordx2 v[98:99], v198, s[48:51], 0 offen
	v_dot2_f32_bf16 v169, v0, v158, 0
	v_dot2_f32_bf16 v171, v1, v159, 0
	v_dot2_f32_bf16 v169, v2, v156, v169
	v_dot2_f32_bf16 v171, v3, v157, v171
	v_dot2_f32_bf16 v169, v4, v154, v169
	v_dot2_f32_bf16 v171, v5, v155, v171
	v_dot2_f32_bf16 v169, v6, v152, v169
	v_dot2_f32_bf16 v171, v7, v153, v171
	v_dot2_f32_bf16 v169, v8, v166, v169
	v_dot2_f32_bf16 v171, v9, v167, v171
	v_dot2_f32_bf16 v169, v10, v164, v169
	v_dot2_f32_bf16 v171, v11, v165, v171
	v_dot2_f32_bf16 v169, v12, v162, v169
	v_dot2_f32_bf16 v171, v13, v163, v171
	v_dot2_f32_bf16 v169, v14, v160, v169
	v_dot2_f32_bf16 v171, v15, v161, v171
	s_waitcnt vmcnt(41)
	v_cvt_scalef32_pk32_bf16_fp6 v[0:15], v[22:27], 1.0
	v_and_b32_e32 v195, 0xffff, v125
	v_lshl_add_u32 v198, v195, 6, v199
	v_lshl_add_u32 v195, v195, 7, v194
	buffer_load_dwordx4 v[22:25], v195, s[48:51], 0 offen
	buffer_load_dwordx2 v[26:27], v198, s[48:51], 0 offen
	v_dot2_f32_bf16 v172, v0, v158, 0
	v_dot2_f32_bf16 v174, v1, v159, 0
	v_dot2_f32_bf16 v172, v2, v156, v172
	v_dot2_f32_bf16 v174, v3, v157, v174
	v_pk_add_f32 v[170:171], v[168:169], v[170:171]
	v_dot2_f32_bf16 v172, v4, v154, v172
	v_dot2_f32_bf16 v174, v5, v155, v174
	v_add_f32_dpp v170, v170, v170 quad_perm:[1,0,3,2] row_mask:0xf bank_mask:0xf bound_ctrl:1
	v_add_f32_dpp v171, v171, v171 quad_perm:[1,0,3,2] row_mask:0xf bank_mask:0xf bound_ctrl:1
	v_dot2_f32_bf16 v172, v6, v152, v172
	v_dot2_f32_bf16 v174, v7, v153, v174
	v_add_f32_dpp v170, v170, v170 quad_perm:[2,3,0,1] row_mask:0xf bank_mask:0xf bound_ctrl:1
	v_add_f32_dpp v171, v171, v171 quad_perm:[2,3,0,1] row_mask:0xf bank_mask:0xf bound_ctrl:1
	v_dot2_f32_bf16 v172, v8, v166, v172
	v_dot2_f32_bf16 v174, v9, v167, v174
	v_add_f32_dpp v170, v170, v170 row_half_mirror row_mask:0xf bank_mask:0xf bound_ctrl:1
	v_add_f32_dpp v171, v171, v171 row_half_mirror row_mask:0xf bank_mask:0xf bound_ctrl:1
	v_dot2_f32_bf16 v172, v10, v164, v172
	v_dot2_f32_bf16 v174, v11, v165, v174
	v_cndmask_b32_e64 v196, 0, v170, s[36:37]
	v_cndmask_b32_e64 v197, 0, v171, s[36:37]
	v_dot2_f32_bf16 v172, v12, v162, v172
	v_dot2_f32_bf16 v174, v13, v163, v174
	v_dot2_f32_bf16 v172, v14, v160, v172
	v_dot2_f32_bf16 v174, v15, v161, v174
	s_waitcnt vmcnt(41)
	v_cvt_scalef32_pk32_bf16_fp6 v[0:15], v[46:51], 1.0
	v_lshrrev_b32_e32 v195, 16, v125
	v_lshl_add_u32 v198, v195, 6, v199
	v_lshl_add_u32 v195, v195, 7, v194
	buffer_load_dwordx4 v[46:49], v195, s[48:51], 0 offen
	buffer_load_dwordx2 v[50:51], v198, s[48:51], 0 offen
	v_dot2_f32_bf16 v173, v0, v158, 0
	v_dot2_f32_bf16 v175, v1, v159, 0
	v_dot2_f32_bf16 v173, v2, v156, v173
	v_dot2_f32_bf16 v175, v3, v157, v175
	v_dot2_f32_bf16 v173, v4, v154, v173
	v_dot2_f32_bf16 v175, v5, v155, v175
	v_dot2_f32_bf16 v173, v6, v152, v173
	v_dot2_f32_bf16 v175, v7, v153, v175
	v_dot2_f32_bf16 v173, v8, v166, v173
	v_dot2_f32_bf16 v175, v9, v167, v175
	v_dot2_f32_bf16 v173, v10, v164, v173
	v_dot2_f32_bf16 v175, v11, v165, v175
	v_dot2_f32_bf16 v173, v12, v162, v173
	v_dot2_f32_bf16 v175, v13, v163, v175
	v_dot2_f32_bf16 v173, v14, v160, v173
	v_dot2_f32_bf16 v175, v15, v161, v175
	s_waitcnt vmcnt(41)
; template <int CTRL> DI float dpp_add(float x) { return x + __uint_as_float(__builtin_amdgcn_update_dpp(0u, __float_as_uint(x), CTRL, 0xf, 0xf, true)); }
; DI int id_of(const u32x4 (&d)[2], int r, unsigned mask = 0xffffu) { const unsigned w = d[r >> 3][(r >> 1) & 3]; return (r & 1) ? (int)((w >> 16) & mask) : (int)(w & mask); }
; #define DOT2(k, acc) acc = __builtin_amdgcn_fdot2_f32_bf16(__builtin_shufflevector(rr, rr, 2 * (k), 2 * (k) + 1), __builtin_bit_cast(bfx2, ((k) & 1) ? hq[(k) >> 1].y : hq[(k) >> 1].x), acc, false)
; DI void eseg_load(ESeg& r, __amdgpu_buffer_rsrc_t rs, int voff) { r.a = __builtin_amdgcn_raw_buffer_load_b128(rs, voff, 0, 0); r.b = __builtin_amdgcn_raw_buffer_load_b64(rs, voff + 16, 0, 0); }
;     ...
;         for (int r = 0; r < 16; ++r) {
;             if (MODE == 2) { o0 += __uint_as_float(rw[r].a.x ^ rw[r].a.w ^ rw[r].b.y); eseg_load(rw[r], US, id_of(idn, r, mask) * ESEG + s24); if (r & 1) __builtin_amdgcn_sched_barrier(0); continue; }
;             typedef __bf16 bfx2 __attribute__((ext_vector_type(2))); typedef __bf16 bfx32 __attribute__((ext_vector_type(32)));
;             const bfx32 rr = __builtin_amdgcn_cvt_scalef32_pk32_bf16_fp6((v6i){(int)rw[r].a.x, (int)rw[r].a.y, (int)rw[r].a.z, (int)rw[r].a.w, (int)rw[r].b.x, (int)rw[r].b.y}, 1.0f);
;             float dA = 0.f, dB = 0.f;
;     ...
;             DOT2(0, dA); DOT2(1, dB); DOT2(2, dA); DOT2(3, dB); DOT2(4, dA); DOT2(5, dB); DOT2(6, dA); DOT2(7, dB); DOT2(8, dA); DOT2(9, dB); DOT2(10, dA); DOT2(11, dB); DOT2(12, dA); DOT2(13, dB); DOT2(14, dA); DOT2(15, dB);
;     ...
;             float d = dA + dB;
;             d = dpp_add<0xB1>(d); d = dpp_add<0x4E>(d); d = dpp_add<0x141>(d);
;             if ((r >> 1) == s) { if (r & 1) o1 = d; else o0 = d; }
;             if (MODE != 1) eseg_load(rw[r], US, id_of(idn, r, mask) * ESEG + s24);
;             else asm volatile("" : "+v"(rw[r].a.x), "+v"(rw[r].a.y), "+v"(rw[r].a.z), "+v"(rw[r].a.w), "+v"(rw[r].b.x), "+v"(rw[r].b.y));
;             if (r & 1) __builtin_amdgcn_sched_barrier(0);
	v_cvt_scalef32_pk32_bf16_fp6 v[0:15], v[28:33], 1.0
	v_and_b32_e32 v195, 0xffff, v126
	v_lshl_add_u32 v198, v195, 6, v199
	v_lshl_add_u32 v195, v195, 7, v194
	buffer_load_dwordx4 v[28:31], v195, s[48:51], 0 offen
	buffer_load_dwordx2 v[32:33], v198, s[48:51], 0 offen
	v_dot2_f32_bf16 v124, v0, v158, 0
	v_dot2_f32_bf16 v176, v1, v159, 0
	v_dot2_f32_bf16 v124, v2, v156, v124
	v_dot2_f32_bf16 v176, v3, v157, v176
	v_pk_add_f32 v[174:175], v[172:173], v[174:175]
	v_dot2_f32_bf16 v124, v4, v154, v124
	v_dot2_f32_bf16 v176, v5, v155, v176
	v_add_f32_dpp v174, v174, v174 quad_perm:[1,0,3,2] row_mask:0xf bank_mask:0xf bound_ctrl:1
	v_add_f32_dpp v175, v175, v175 quad_perm:[1,0,3,2] row_mask:0xf bank_mask:0xf bound_ctrl:1
	v_dot2_f32_bf16 v124, v6, v152, v124
	v_dot2_f32_bf16 v176, v7, v153, v176
	v_add_f32_dpp v174, v174, v174 quad_perm:[2,3,0,1] row_mask:0xf bank_mask:0xf bound_ctrl:1
	v_add_f32_dpp v175, v175, v175 quad_perm:[2,3,0,1] row_mask:0xf bank_mask:0xf bound_ctrl:1
	v_dot2_f32_bf16 v124, v8, v166, v124
	v_dot2_f32_bf16 v176, v9, v167, v176
	v_add_f32_dpp v174, v174, v174 row_half_mirror row_mask:0xf bank_mask:0xf bound_ctrl:1
	v_add_f32_dpp v175, v175, v175 row_half_mirror row_mask:0xf bank_mask:0xf bound_ctrl:1
	v_dot2_f32_bf16 v124, v10, v164, v124
	v_dot2_f32_bf16 v176, v11, v165, v176
	v_cndmask_b32_e64 v196, v196, v174, s[38:39]
	v_cndmask_b32_e64 v197, v197, v175, s[38:39]
	v_dot2_f32_bf16 v124, v12, v162, v124
	v_dot2_f32_bf16 v176, v13, v163, v176
	v_dot2_f32_bf16 v124, v14, v160, v124
	v_dot2_f32_bf16 v176, v15, v161, v176
	s_waitcnt vmcnt(41)
	v_cvt_scalef32_pk32_bf16_fp6 v[0:15], v[64:69], 1.0
	v_lshrrev_b32_e32 v195, 16, v126
	v_lshl_add_u32 v198, v195, 6, v199
	v_lshl_add_u32 v195, v195, 7, v194
	buffer_load_dwordx4 v[64:67], v195, s[48:51], 0 offen
	buffer_load_dwordx2 v[68:69], v198, s[48:51], 0 offen
	v_dot2_f32_bf16 v125, v0, v158, 0
	v_dot2_f32_bf16 v177, v1, v159, 0
	v_dot2_f32_bf16 v125, v2, v156, v125
	v_dot2_f32_bf16 v177, v3, v157, v177
	v_dot2_f32_bf16 v125, v4, v154, v125
	v_dot2_f32_bf16 v177, v5, v155, v177
	v_dot2_f32_bf16 v125, v6, v152, v125
	v_dot2_f32_bf16 v177, v7, v153, v177
	v_dot2_f32_bf16 v125, v8, v166, v125
	v_dot2_f32_bf16 v177, v9, v167, v177
	v_dot2_f32_bf16 v125, v10, v164, v125
	v_dot2_f32_bf16 v177, v11, v165, v177
	v_dot2_f32_bf16 v125, v12, v162, v125
	v_dot2_f32_bf16 v177, v13, v163, v177
	v_dot2_f32_bf16 v125, v14, v160, v125
	v_dot2_f32_bf16 v177, v15, v161, v177
	s_waitcnt vmcnt(41)
	v_cvt_scalef32_pk32_bf16_fp6 v[0:15], v[34:39], 1.0
	v_and_b32_e32 v195, 0xffff, v127
	v_lshl_add_u32 v198, v195, 6, v199
	v_lshl_add_u32 v195, v195, 7, v194
	buffer_load_dwordx4 v[34:37], v195, s[48:51], 0 offen
	buffer_load_dwordx2 v[38:39], v198, s[48:51], 0 offen
	v_dot2_f32_bf16 v178, v0, v158, 0
	v_dot2_f32_bf16 v180, v1, v159, 0
	v_dot2_f32_bf16 v178, v2, v156, v178
	v_dot2_f32_bf16 v180, v3, v157, v180
	v_pk_add_f32 v[176:177], v[124:125], v[176:177]
	v_dot2_f32_bf16 v178, v4, v154, v178
	v_dot2_f32_bf16 v180, v5, v155, v180
	v_add_f32_dpp v176, v176, v176 quad_perm:[1,0,3,2] row_mask:0xf bank_mask:0xf bound_ctrl:1
	v_add_f32_dpp v177, v177, v177 quad_perm:[1,0,3,2] row_mask:0xf bank_mask:0xf bound_ctrl:1
	v_dot2_f32_bf16 v178, v6, v152, v178
	v_dot2_f32_bf16 v180, v7, v153, v180
	v_add_f32_dpp v176, v176, v176 quad_perm:[2,3,0,1] row_mask:0xf bank_mask:0xf bound_ctrl:1
	v_add_f32_dpp v177, v177, v177 quad_perm:[2,3,0,1] row_mask:0xf bank_mask:0xf bound_ctrl:1
	v_dot2_f32_bf16 v178, v8, v166, v178
	v_dot2_f32_bf16 v180, v9, v167, v180
	v_add_f32_dpp v176, v176, v176 row_half_mirror row_mask:0xf bank_mask:0xf bound_ctrl:1
	v_add_f32_dpp v177, v177, v177 row_half_mirror row_mask:0xf bank_mask:0xf bound_ctrl:1
	v_dot2_f32_bf16 v178, v10, v164, v178
	v_dot2_f32_bf16 v180, v11, v165, v180
	v_cndmask_b32_e64 v196, v196, v176, s[40:41]
	v_cndmask_b32_e64 v197, v197, v177, s[40:41]
	v_dot2_f32_bf16 v178, v12, v162, v178
	v_dot2_f32_bf16 v180, v13, v163, v180
	v_dot2_f32_bf16 v178, v14, v160, v178
	v_dot2_f32_bf16 v180, v15, v161, v180
	s_waitcnt vmcnt(41)
	v_cvt_scalef32_pk32_bf16_fp6 v[0:15], v[76:81], 1.0
	v_lshrrev_b32_e32 v195, 16, v127
	v_lshl_add_u32 v198, v195, 6, v199
	v_lshl_add_u32 v195, v195, 7, v194
	buffer_load_dwordx4 v[76:79], v195, s[48:51], 0 offen
	buffer_load_dwordx2 v[80:81], v198, s[48:51], 0 offen
	v_dot2_f32_bf16 v179, v0, v158, 0
	v_dot2_f32_bf16 v181, v1, v159, 0
	v_dot2_f32_bf16 v179, v2, v156, v179
	v_dot2_f32_bf16 v181, v3, v157, v181
	v_dot2_f32_bf16 v179, v4, v154, v179
	v_dot2_f32_bf16 v181, v5, v155, v181
	v_dot2_f32_bf16 v179, v6, v152, v179
	v_dot2_f32_bf16 v181, v7, v153, v181
	v_dot2_f32_bf16 v179, v8, v166, v179
	v_dot2_f32_bf16 v181, v9, v167, v181
	v_dot2_f32_bf16 v179, v10, v164, v179
	v_dot2_f32_bf16 v181, v11, v165, v181
	v_dot2_f32_bf16 v179, v12, v162, v179
	v_dot2_f32_bf16 v181, v13, v163, v181
	v_dot2_f32_bf16 v179, v14, v160, v179
	v_dot2_f32_bf16 v181, v15, v161, v181
	s_waitcnt vmcnt(41)
; template <int CTRL> DI float dpp_add(float x) { return x + __uint_as_float(__builtin_amdgcn_update_dpp(0u, __float_as_uint(x), CTRL, 0xf, 0xf, true)); }
; DI int id_of(const u32x4 (&d)[2], int r, unsigned mask = 0xffffu) { const unsigned w = d[r >> 3][(r >> 1) & 3]; return (r & 1) ? (int)((w >> 16) & mask) : (int)(w & mask); }
; #define DOT2(k, acc) acc = __builtin_amdgcn_fdot2_f32_bf16(__builtin_shufflevector(rr, rr, 2 * (k), 2 * (k) + 1), __builtin_bit_cast(bfx2, ((k) & 1) ? hq[(k) >> 1].y : hq[(k) >> 1].x), acc, false)
; DI void eseg_load(ESeg& r, __amdgpu_buffer_rsrc_t rs, int voff) { r.a = __builtin_amdgcn_raw_buffer_load_b128(rs, voff, 0, 0); r.b = __builtin_amdgcn_raw_buffer_load_b64(rs, voff + 16, 0, 0); }
;     ...
;         for (int r = 0; r < 16; ++r) {
;             if (MODE == 2) { o0 += __uint_as_float(rw[r].a.x ^ rw[r].a.w ^ rw[r].b.y); eseg_load(rw[r], US, id_of(idn, r, mask) * ESEG + s24); if (r & 1) __builtin_amdgcn_sched_barrier(0); continue; }
;             typedef __bf16 bfx2 __attribute__((ext_vector_type(2))); typedef __bf16 bfx32 __attribute__((ext_vector_type(32)));
;             const bfx32 rr = __builtin_amdgcn_cvt_scalef32_pk32_bf16_fp6((v6i){(int)rw[r].a.x, (int)rw[r].a.y, (int)rw[r].a.z, (int)rw[r].a.w, (int)rw[r].b.x, (int)rw[r].b.y}, 1.0f);
;             float dA = 0.f, dB = 0.f;
;     ...
;             DOT2(0, dA); DOT2(1, dB); DOT2(2, dA); DOT2(3, dB); DOT2(4, dA); DOT2(5, dB); DOT2(6, dA); DOT2(7, dB); DOT2(8, dA); DOT2(9, dB); DOT2(10, dA); DOT2(11, dB); DOT2(12, dA); DOT2(13, dB); DOT2(14, dA); DOT2(15, dB);
;     ...
;             float d = dA + dB;
;             d = dpp_add<0xB1>(d); d = dpp_add<0x4E>(d); d = dpp_add<0x141>(d);
;             if ((r >> 1) == s) { if (r & 1) o1 = d; else o0 = d; }
;             if (MODE != 1) eseg_load(rw[r], US, id_of(idn, r, mask) * ESEG + s24);
;             else asm volatile("" : "+v"(rw[r].a.x), "+v"(rw[r].a.y), "+v"(rw[r].a.z), "+v"(rw[r].a.w), "+v"(rw[r].b.x), "+v"(rw[r].b.y));
;             if (r & 1) __builtin_amdgcn_sched_barrier(0);
	v_cvt_scalef32_pk32_bf16_fp6 v[0:15], v[40:45], 1.0
	v_and_b32_e32 v195, 0xffff, v120
	v_lshl_add_u32 v198, v195, 6, v199
	v_lshl_add_u32 v195, v195, 7, v194
	buffer_load_dwordx4 v[40:43], v195, s[48:51], 0 offen
	buffer_load_dwordx2 v[44:45], v198, s[48:51], 0 offen
	v_dot2_f32_bf16 v126, v0, v158, 0
	v_dot2_f32_bf16 v182, v1, v159, 0
	v_dot2_f32_bf16 v126, v2, v156, v126
	v_dot2_f32_bf16 v182, v3, v157, v182
	v_pk_add_f32 v[180:181], v[178:179], v[180:181]
	v_dot2_f32_bf16 v126, v4, v154, v126
	v_dot2_f32_bf16 v182, v5, v155, v182
	v_add_f32_dpp v180, v180, v180 quad_perm:[1,0,3,2] row_mask:0xf bank_mask:0xf bound_ctrl:1
	v_add_f32_dpp v181, v181, v181 quad_perm:[1,0,3,2] row_mask:0xf bank_mask:0xf bound_ctrl:1
	v_dot2_f32_bf16 v126, v6, v152, v126
	v_dot2_f32_bf16 v182, v7, v153, v182
	v_add_f32_dpp v180, v180, v180 quad_perm:[2,3,0,1] row_mask:0xf bank_mask:0xf bound_ctrl:1
	v_add_f32_dpp v181, v181, v181 quad_perm:[2,3,0,1] row_mask:0xf bank_mask:0xf bound_ctrl:1
	v_dot2_f32_bf16 v126, v8, v166, v126
	v_dot2_f32_bf16 v182, v9, v167, v182
	v_add_f32_dpp v180, v180, v180 row_half_mirror row_mask:0xf bank_mask:0xf bound_ctrl:1
	v_add_f32_dpp v181, v181, v181 row_half_mirror row_mask:0xf bank_mask:0xf bound_ctrl:1
	v_dot2_f32_bf16 v126, v10, v164, v126
	v_dot2_f32_bf16 v182, v11, v165, v182
	v_cndmask_b32_e64 v196, v196, v180, s[42:43]
	v_cndmask_b32_e64 v197, v197, v181, s[42:43]
	v_dot2_f32_bf16 v126, v12, v162, v126
	v_dot2_f32_bf16 v182, v13, v163, v182
	v_dot2_f32_bf16 v126, v14, v160, v126
	v_dot2_f32_bf16 v182, v15, v161, v182
	s_waitcnt vmcnt(41)
	v_cvt_scalef32_pk32_bf16_fp6 v[0:15], v[82:87], 1.0
	v_lshrrev_b32_e32 v195, 16, v120
	v_lshl_add_u32 v198, v195, 6, v199
	v_lshl_add_u32 v195, v195, 7, v194
	buffer_load_dwordx4 v[82:85], v195, s[48:51], 0 offen
	buffer_load_dwordx2 v[86:87], v198, s[48:51], 0 offen
	v_dot2_f32_bf16 v127, v0, v158, 0
	v_dot2_f32_bf16 v183, v1, v159, 0
	v_dot2_f32_bf16 v127, v2, v156, v127
	v_dot2_f32_bf16 v183, v3, v157, v183
	v_dot2_f32_bf16 v127, v4, v154, v127
	v_dot2_f32_bf16 v183, v5, v155, v183
	v_dot2_f32_bf16 v127, v6, v152, v127
	v_dot2_f32_bf16 v183, v7, v153, v183
	v_dot2_f32_bf16 v127, v8, v166, v127
	v_dot2_f32_bf16 v183, v9, v167, v183
	v_dot2_f32_bf16 v127, v10, v164, v127
	v_dot2_f32_bf16 v183, v11, v165, v183
	v_dot2_f32_bf16 v127, v12, v162, v127
	v_dot2_f32_bf16 v183, v13, v163, v183
	v_dot2_f32_bf16 v127, v14, v160, v127
	v_dot2_f32_bf16 v183, v15, v161, v183
	s_waitcnt vmcnt(41)
	v_cvt_scalef32_pk32_bf16_fp6 v[0:15], v[58:63], 1.0
	v_and_b32_e32 v195, 0xffff, v121
	v_lshl_add_u32 v198, v195, 6, v199
	v_lshl_add_u32 v195, v195, 7, v194
	buffer_load_dwordx4 v[58:61], v195, s[48:51], 0 offen
	buffer_load_dwordx2 v[62:63], v198, s[48:51], 0 offen
	v_dot2_f32_bf16 v184, v0, v158, 0
	v_dot2_f32_bf16 v186, v1, v159, 0
	v_dot2_f32_bf16 v184, v2, v156, v184
	v_dot2_f32_bf16 v186, v3, v157, v186
	v_pk_add_f32 v[182:183], v[126:127], v[182:183]
	v_dot2_f32_bf16 v184, v4, v154, v184
	v_dot2_f32_bf16 v186, v5, v155, v186
	v_add_f32_dpp v182, v182, v182 quad_perm:[1,0,3,2] row_mask:0xf bank_mask:0xf bound_ctrl:1
	v_add_f32_dpp v183, v183, v183 quad_perm:[1,0,3,2] row_mask:0xf bank_mask:0xf bound_ctrl:1
	v_dot2_f32_bf16 v184, v6, v152, v184
	v_dot2_f32_bf16 v186, v7, v153, v186
	v_add_f32_dpp v182, v182, v182 quad_perm:[2,3,0,1] row_mask:0xf bank_mask:0xf bound_ctrl:1
	v_add_f32_dpp v183, v183, v183 quad_perm:[2,3,0,1] row_mask:0xf bank_mask:0xf bound_ctrl:1
	v_dot2_f32_bf16 v184, v8, v166, v184
	v_dot2_f32_bf16 v186, v9, v167, v186
	v_add_f32_dpp v182, v182, v182 row_half_mirror row_mask:0xf bank_mask:0xf bound_ctrl:1
	v_add_f32_dpp v183, v183, v183 row_half_mirror row_mask:0xf bank_mask:0xf bound_ctrl:1
	v_dot2_f32_bf16 v184, v10, v164, v184
	v_dot2_f32_bf16 v186, v11, v165, v186
	v_cndmask_b32_e64 v196, v196, v182, s[44:45]
	v_cndmask_b32_e64 v197, v197, v183, s[44:45]
	v_dot2_f32_bf16 v184, v12, v162, v184
	v_dot2_f32_bf16 v186, v13, v163, v186
	v_dot2_f32_bf16 v184, v14, v160, v184
	v_dot2_f32_bf16 v186, v15, v161, v186
	s_waitcnt vmcnt(41)
	v_cvt_scalef32_pk32_bf16_fp6 v[0:15], v[88:93], 1.0
	v_lshrrev_b32_e32 v195, 16, v121
	v_lshl_add_u32 v198, v195, 6, v199
	v_lshl_add_u32 v195, v195, 7, v194
	buffer_load_dwordx4 v[88:91], v195, s[48:51], 0 offen
	buffer_load_dwordx2 v[92:93], v198, s[48:51], 0 offen
	v_dot2_f32_bf16 v185, v0, v158, 0
	v_dot2_f32_bf16 v187, v1, v159, 0
	v_dot2_f32_bf16 v185, v2, v156, v185
	v_dot2_f32_bf16 v187, v3, v157, v187
	v_dot2_f32_bf16 v185, v4, v154, v185
	v_dot2_f32_bf16 v187, v5, v155, v187
	v_dot2_f32_bf16 v185, v6, v152, v185
	v_dot2_f32_bf16 v187, v7, v153, v187
	v_dot2_f32_bf16 v185, v8, v166, v185
	v_dot2_f32_bf16 v187, v9, v167, v187
	v_dot2_f32_bf16 v185, v10, v164, v185
	v_dot2_f32_bf16 v187, v11, v165, v187
	v_dot2_f32_bf16 v185, v12, v162, v185
	v_dot2_f32_bf16 v187, v13, v163, v187
	v_dot2_f32_bf16 v185, v14, v160, v185
	v_dot2_f32_bf16 v187, v15, v161, v187
	s_waitcnt vmcnt(41)
; template <int CTRL> DI float dpp_add(float x) { return x + __uint_as_float(__builtin_amdgcn_update_dpp(0u, __float_as_uint(x), CTRL, 0xf, 0xf, true)); }
; DI int id_of(const u32x4 (&d)[2], int r, unsigned mask = 0xffffu) { const unsigned w = d[r >> 3][(r >> 1) & 3]; return (r & 1) ? (int)((w >> 16) & mask) : (int)(w & mask); }
; #define DOT2(k, acc) acc = __builtin_amdgcn_fdot2_f32_bf16(__builtin_shufflevector(rr, rr, 2 * (k), 2 * (k) + 1), __builtin_bit_cast(bfx2, ((k) & 1) ? hq[(k) >> 1].y : hq[(k) >> 1].x), acc, false)
; DI void eseg_load(ESeg& r, __amdgpu_buffer_rsrc_t rs, int voff) { r.a = __builtin_amdgcn_raw_buffer_load_b128(rs, voff, 0, 0); r.b = __builtin_amdgcn_raw_buffer_load_b64(rs, voff + 16, 0, 0); }
;     ...
;         for (int r = 0; r < 16; ++r) {
;             if (MODE == 2) { o0 += __uint_as_float(rw[r].a.x ^ rw[r].a.w ^ rw[r].b.y); eseg_load(rw[r], US, id_of(idn, r, mask) * ESEG + s24); if (r & 1) __builtin_amdgcn_sched_barrier(0); continue; }
;             typedef __bf16 bfx2 __attribute__((ext_vector_type(2))); typedef __bf16 bfx32 __attribute__((ext_vector_type(32)));
;             const bfx32 rr = __builtin_amdgcn_cvt_scalef32_pk32_bf16_fp6((v6i){(int)rw[r].a.x, (int)rw[r].a.y, (int)rw[r].a.z, (int)rw[r].a.w, (int)rw[r].b.x, (int)rw[r].b.y}, 1.0f);
;             float dA = 0.f, dB = 0.f;
;     ...
;             DOT2(0, dA); DOT2(1, dB); DOT2(2, dA); DOT2(3, dB); DOT2(4, dA); DOT2(5, dB); DOT2(6, dA); DOT2(7, dB); DOT2(8, dA); DOT2(9, dB); DOT2(10, dA); DOT2(11, dB); DOT2(12, dA); DOT2(13, dB); DOT2(14, dA); DOT2(15, dB);
;     ...
;             float d = dA + dB;
;             d = dpp_add<0xB1>(d); d = dpp_add<0x4E>(d); d = dpp_add<0x141>(d);
;             if ((r >> 1) == s) { if (r & 1) o1 = d; else o0 = d; }
;             if (MODE != 1) eseg_load(rw[r], US, id_of(idn, r, mask) * ESEG + s24);
;             else asm volatile("" : "+v"(rw[r].a.x), "+v"(rw[r].a.y), "+v"(rw[r].a.z), "+v"(rw[r].a.w), "+v"(rw[r].b.x), "+v"(rw[r].b.y));
;             if (r & 1) __builtin_amdgcn_sched_barrier(0);
;         }
;         *(f32x2*)(P + (size_t)t * 128 + g * 16 + 2 * s) = (f32x2){o0, o1};
;         if (tn >= nrows) break;
;         t = tn; idn[0] = idnn[0]; idn[1] = idnn[1];
	v_cvt_scalef32_pk32_bf16_fp6 v[0:15], v[70:75], 1.0
	v_and_b32_e32 v195, 0xffff, v122
	v_lshl_add_u32 v198, v195, 6, v199
	v_lshl_add_u32 v195, v195, 7, v194
	buffer_load_dwordx4 v[70:73], v195, s[48:51], 0 offen
	buffer_load_dwordx2 v[74:75], v198, s[48:51], 0 offen
	v_dot2_f32_bf16 v120, v0, v158, 0
	v_dot2_f32_bf16 v188, v1, v159, 0
	v_dot2_f32_bf16 v120, v2, v156, v120
	v_dot2_f32_bf16 v188, v3, v157, v188
	v_pk_add_f32 v[186:187], v[184:185], v[186:187]
	v_dot2_f32_bf16 v120, v4, v154, v120
	v_dot2_f32_bf16 v188, v5, v155, v188
	v_add_f32_dpp v186, v186, v186 quad_perm:[1,0,3,2] row_mask:0xf bank_mask:0xf bound_ctrl:1
	v_add_f32_dpp v187, v187, v187 quad_perm:[1,0,3,2] row_mask:0xf bank_mask:0xf bound_ctrl:1
	v_dot2_f32_bf16 v120, v6, v152, v120
	v_dot2_f32_bf16 v188, v7, v153, v188
	v_add_f32_dpp v186, v186, v186 quad_perm:[2,3,0,1] row_mask:0xf bank_mask:0xf bound_ctrl:1
	v_add_f32_dpp v187, v187, v187 quad_perm:[2,3,0,1] row_mask:0xf bank_mask:0xf bound_ctrl:1
	v_dot2_f32_bf16 v120, v8, v166, v120
	v_dot2_f32_bf16 v188, v9, v167, v188
	v_add_f32_dpp v186, v186, v186 row_half_mirror row_mask:0xf bank_mask:0xf bound_ctrl:1
	v_add_f32_dpp v187, v187, v187 row_half_mirror row_mask:0xf bank_mask:0xf bound_ctrl:1
	v_dot2_f32_bf16 v120, v10, v164, v120
	v_dot2_f32_bf16 v188, v11, v165, v188
	v_cndmask_b32_e64 v196, v196, v186, s[46:47]
	v_cndmask_b32_e64 v197, v197, v187, s[46:47]
	v_dot2_f32_bf16 v120, v12, v162, v120
	v_dot2_f32_bf16 v188, v13, v163, v188
	v_dot2_f32_bf16 v120, v14, v160, v120
	v_dot2_f32_bf16 v188, v15, v161, v188
	s_waitcnt vmcnt(41)
	v_cvt_scalef32_pk32_bf16_fp6 v[0:15], v[100:105], 1.0
	v_lshrrev_b32_e32 v195, 16, v122
	v_lshl_add_u32 v198, v195, 6, v199
	v_lshl_add_u32 v195, v195, 7, v194
	buffer_load_dwordx4 v[100:103], v195, s[48:51], 0 offen
	buffer_load_dwordx2 v[104:105], v198, s[48:51], 0 offen
	v_dot2_f32_bf16 v121, v0, v158, 0
	v_dot2_f32_bf16 v189, v1, v159, 0
	v_dot2_f32_bf16 v121, v2, v156, v121
	v_dot2_f32_bf16 v189, v3, v157, v189
	v_dot2_f32_bf16 v121, v4, v154, v121
	v_dot2_f32_bf16 v189, v5, v155, v189
	v_dot2_f32_bf16 v121, v6, v152, v121
	v_dot2_f32_bf16 v189, v7, v153, v189
	v_dot2_f32_bf16 v121, v8, v166, v121
	v_dot2_f32_bf16 v189, v9, v167, v189
	v_dot2_f32_bf16 v121, v10, v164, v121
	v_dot2_f32_bf16 v189, v11, v165, v189
	v_dot2_f32_bf16 v121, v12, v162, v121
	v_dot2_f32_bf16 v189, v13, v163, v189
	v_dot2_f32_bf16 v121, v14, v160, v121
	v_dot2_f32_bf16 v189, v15, v161, v189
	s_waitcnt vmcnt(41)
	v_cvt_scalef32_pk32_bf16_fp6 v[0:15], v[52:57], 1.0
	v_and_b32_e32 v195, 0xffff, v123
	v_lshl_add_u32 v198, v195, 6, v199
	v_lshl_add_u32 v195, v195, 7, v194
	buffer_load_dwordx4 v[52:55], v195, s[48:51], 0 offen
	buffer_load_dwordx2 v[56:57], v198, s[48:51], 0 offen
	v_dot2_f32_bf16 v190, v0, v158, 0
	v_dot2_f32_bf16 v192, v1, v159, 0
	v_dot2_f32_bf16 v190, v2, v156, v190
	v_dot2_f32_bf16 v192, v3, v157, v192
	v_pk_add_f32 v[188:189], v[120:121], v[188:189]
	v_dot2_f32_bf16 v190, v4, v154, v190
	v_dot2_f32_bf16 v192, v5, v155, v192
	v_add_f32_dpp v188, v188, v188 quad_perm:[1,0,3,2] row_mask:0xf bank_mask:0xf bound_ctrl:1
	v_add_f32_dpp v189, v189, v189 quad_perm:[1,0,3,2] row_mask:0xf bank_mask:0xf bound_ctrl:1
	v_dot2_f32_bf16 v190, v6, v152, v190
	v_dot2_f32_bf16 v192, v7, v153, v192
	v_add_f32_dpp v188, v188, v188 quad_perm:[2,3,0,1] row_mask:0xf bank_mask:0xf bound_ctrl:1
	v_add_f32_dpp v189, v189, v189 quad_perm:[2,3,0,1] row_mask:0xf bank_mask:0xf bound_ctrl:1
	v_dot2_f32_bf16 v190, v8, v166, v190
	v_dot2_f32_bf16 v192, v9, v167, v192
	v_add_f32_dpp v188, v188, v188 row_half_mirror row_mask:0xf bank_mask:0xf bound_ctrl:1
	v_add_f32_dpp v189, v189, v189 row_half_mirror row_mask:0xf bank_mask:0xf bound_ctrl:1
	v_dot2_f32_bf16 v190, v10, v164, v190
	v_dot2_f32_bf16 v192, v11, v165, v192
	v_cndmask_b32_e64 v196, v196, v188, s[0:1]
	v_cndmask_b32_e64 v197, v197, v189, s[0:1]
	v_dot2_f32_bf16 v190, v12, v162, v190
	v_dot2_f32_bf16 v192, v13, v163, v192
	v_dot2_f32_bf16 v190, v14, v160, v190
	v_dot2_f32_bf16 v192, v15, v161, v192
	s_waitcnt vmcnt(41)
	v_cvt_scalef32_pk32_bf16_fp6 v[0:15], v[106:111], 1.0
	v_lshrrev_b32_e32 v195, 16, v123
	v_lshl_add_u32 v198, v195, 6, v199
	v_lshl_add_u32 v195, v195, 7, v194
	buffer_load_dwordx4 v[106:109], v195, s[48:51], 0 offen
	buffer_load_dwordx2 v[110:111], v198, s[48:51], 0 offen
	v_dot2_f32_bf16 v191, v0, v158, 0
	v_dot2_f32_bf16 v193, v1, v159, 0
	v_dot2_f32_bf16 v191, v2, v156, v191
	v_dot2_f32_bf16 v193, v3, v157, v193
	v_dot2_f32_bf16 v191, v4, v154, v191
	v_dot2_f32_bf16 v193, v5, v155, v193
	v_dot2_f32_bf16 v191, v6, v152, v191
	v_dot2_f32_bf16 v193, v7, v153, v193
	v_dot2_f32_bf16 v191, v8, v166, v191
	v_dot2_f32_bf16 v193, v9, v167, v193
	v_dot2_f32_bf16 v191, v10, v164, v191
	v_dot2_f32_bf16 v193, v11, v165, v193
	v_dot2_f32_bf16 v191, v12, v162, v191
	v_dot2_f32_bf16 v193, v13, v163, v193
	v_dot2_f32_bf16 v191, v14, v160, v191
	v_dot2_f32_bf16 v193, v15, v161, v193
	s_waitcnt vmcnt(32)
	v_mov_b64_e32 v[122:123], v[114:115]
	v_mov_b64_e32 v[126:127], v[118:119]
	v_mov_b64_e32 v[120:121], v[112:113]
	v_mov_b64_e32 v[124:125], v[116:117]
	v_pk_add_f32 v[192:193], v[190:191], v[192:193]
	v_mov_b64_e32 v[160:161], v[150:151]
	v_mov_b64_e32 v[162:163], v[148:149]
	v_add_f32_dpp v192, v192, v192 quad_perm:[1,0,3,2] row_mask:0xf bank_mask:0xf bound_ctrl:1
	v_add_f32_dpp v193, v193, v193 quad_perm:[1,0,3,2] row_mask:0xf bank_mask:0xf bound_ctrl:1
	v_mov_b64_e32 v[164:165], v[146:147]
	v_mov_b64_e32 v[166:167], v[144:145]
	v_add_f32_dpp v192, v192, v192 quad_perm:[2,3,0,1] row_mask:0xf bank_mask:0xf bound_ctrl:1
	v_add_f32_dpp v193, v193, v193 quad_perm:[2,3,0,1] row_mask:0xf bank_mask:0xf bound_ctrl:1
	v_mov_b64_e32 v[152:153], v[142:143]
	v_mov_b64_e32 v[154:155], v[140:141]
	v_add_f32_dpp v192, v192, v192 row_half_mirror row_mask:0xf bank_mask:0xf bound_ctrl:1
	v_add_f32_dpp v193, v193, v193 row_half_mirror row_mask:0xf bank_mask:0xf bound_ctrl:1
	v_mov_b64_e32 v[156:157], v[138:139]
	v_mov_b64_e32 v[158:159], v[136:137]
	v_cndmask_b32_e64 v196, v196, v192, s[2:3]
	v_cndmask_b32_e64 v197, v197, v193, s[2:3]
	global_store_dwordx2 v[134:135], v[196:197], off
	v_lshl_add_u64 v[134:135], v[134:135], 0, s[6:7]
	s_and_b64 vcc, s[8:9], exec
	s_mov_b32 s10, s11
	s_cbranch_vccnz .LBB0_979

; DI void eseg_load(ESeg& r, __amdgpu_buffer_rsrc_t rs, int voff) { r.a = __builtin_amdgcn_raw_buffer_load_b128(rs, voff, 0, 0); r.b = __builtin_amdgcn_raw_buffer_load_b64(rs, voff + 16, 0, 0); }
; DI int id_of(const u32x4 (&d)[2], int r, unsigned mask = 0xffffu) { const unsigned w = d[r >> 3][(r >> 1) & 3]; return (r & 1) ? (int)((w >> 16) & mask) : (int)(w & mask); }
;     ...
;     int x, wx, nwx; xcd_split(F, x, wx, nwx);
;     const int lane = F.lane, s = lane & 7, g = lane >> 3, s24 = s * 24;
;     const __amdgpu_buffer_rsrc_t VS = __builtin_amdgcn_make_buffer_rsrc((void*)uniform_ptr((unsigned char*)F.V + (size_t)x * ESLICE), 0, (int)ESLICE, 0x00020000);
;     const unsigned short* RI16 = (const unsigned short*)(F.ws + WS_RIDX); const float* Wg = (const float*)(F.ws + WS_PW) + g * 16;
;     const bool b3 = (lane >> 3) & 1; const int col = (((lane >> 5) * 2 + ((lane >> 4) & 1)) * 2 + (b3 ? 1 : 0)) * 256 + (8 * x + s) * 4;
;     int t = wx; if (t >= nrows) return;
;     ESeg rw[16]; u32x4 idn[2], idnn[2]; f32x4 wq[4];
;     { u32x4 idc[2]; ids_load(idc, RI16, t, g);
; #pragma unroll
;       for (int r = 0; r < 16; ++r) eseg_load(rw[r], VS, id_of(idc, r, mask) * ESEG + s24); }
; #pragma unroll
;     for (int q = 0; q < 4; ++q) wq[q] = *(const f32x4*)(Wg + (size_t)t * 128 + q * 4);
;     ids_load(idn, RI16, t + nwx < nrows ? t + nwx : t, g);
;     __builtin_amdgcn_s_waitcnt(0);
.LBB0_1092:
	s_andn2_b64 vcc, exec, s[0:1]
	s_cbranch_vccnz .LBB0_1148
	s_waitcnt vmcnt(0)
	v_mov_b32_e32 v0, v129
	v_readlane_b32 s0, v253, 54
	v_mbcnt_lo_u32_b32 v0, -1, v0
	v_mbcnt_hi_u32_b32 v2, -1, v0
	s_mov_b32 s3, s88
	v_mov_b32_e32 v0, s0
	s_load_dword s2, s[90:91], 0x0
	ds_read_b64 v[0:1], v0
	s_waitcnt lgkmcnt(0)
	v_mov_b32_e32 v0, s79
	ds_read_b64 v[0:1], v0
	v_readlane_b32 s1, v252, 0
	v_readlane_b32 s0, v253, 33
	s_add_i32 s1, s3, s1
	s_add_i32 s0, s3, s0
	s_waitcnt lgkmcnt(0)
	v_readfirstlane_b32 s5, v1
	v_readfirstlane_b32 s4, v0
	s_ashr_i32 s1, s1, 3
	v_and_b32_e64 v0, s2, 7
	v_and_b32_e32 v1, 8, v2
	v_cmp_eq_u32_e32 vcc, 0, v1
	v_mov_b32_e32 v1, s1
	v_mov_b32_e32 v3, s0
	v_cmp_eq_u32_e64 s[0:1], 0, v0
	s_nop 1
	v_cndmask_b32_e64 v0, v1, v3, s[0:1]
	v_mov_b32_e32 v1, s3
	v_mov_b32_e32 v3, s80
	v_cndmask_b32_e64 v1, v1, v3, s[0:1]
	v_and_b32_e32 v3, 7, v1
	v_mul_u32_u24_e32 v128, 0x300000, v3
	v_lshl_add_u64 v[4:5], s[4:5], 0, v[128:129]
	s_mov_b64 s[0:1], 0x8c00000
	v_lshl_add_u64 v[4:5], v[4:5], 0, s[0:1]
	v_cmp_gt_i32_e64 s[0:1], s15, v0
	v_readfirstlane_b32 s3, v5
	v_readfirstlane_b32 s48, v4
	s_and_saveexec_b64 s[6:7], s[0:1]
	s_movk_i32 s12, 0xc0
	s_movk_i32 s13, 0x4000
	s_mov_b32 s14, 0x3fb504f3
	s_cbranch_execz .LBB0_1096
	v_lshlrev_b32_e32 v1, 1, v2
	s_and_b32 s49, s3, 0xffff
	v_and_b32_e32 v12, -16, v1
	s_add_u32 s8, s4, 0x42c00000
	v_ashrrev_i32_e32 v1, 31, v0
	v_ashrrev_i32_e32 v13, 31, v12
	s_addc_u32 s9, s5, 0
	v_lshlrev_b64 v[4:5], 8, v[0:1]
	v_lshl_add_u64 v[4:5], s[8:9], 0, v[4:5]
	v_lshlrev_b64 v[14:15], 1, v[12:13]
	v_lshl_add_u64 v[8:9], v[4:5], 0, v[14:15]
	global_load_dwordx4 v[4:7], v[8:9], off
	s_nop 0
	global_load_dwordx4 v[8:11], v[8:9], off offset:16
	v_lshl_add_u64 v[12:13], v[12:13], 2, s[4:5]
	s_mov_b64 s[0:1], 0x3e400000
	v_lshlrev_b64 v[16:17], 9, v[0:1]
	v_lshl_add_u64 v[214:215], v[12:13], 0, s[0:1]
	v_and_b32_e32 v18, 7, v2
	v_lshl_add_u64 v[12:13], v[214:215], 0, v[16:17]
	v_lshlrev_b32_e32 v128, 4, v18
	v_lshlrev_b32_e32 v222, 3, v18
	v_add_u32_e32 v222, 0x200000, v222
	global_load_dwordx4 v[162:165], v[12:13], off offset:48
	global_load_dwordx4 v[174:177], v[12:13], off offset:32
	global_load_dwordx4 v[190:193], v[12:13], off offset:16
	global_load_dwordx4 v[178:181], v[12:13], off
	v_add_u32_e32 v19, s2, v0
	v_cmp_gt_i32_e64 s[0:1], s15, v19
	v_lshlrev_b32_e32 v2, 5, v2
	s_ashr_i32 s3, s2, 31
	v_lshl_add_u64 v[218:219], s[8:9], 0, v[14:15]
	s_mov_b64 s[10:11], 0
	s_waitcnt vmcnt(5)
	v_and_b32_e32 v12, 0xffff, v4
	v_lshrrev_b32_e32 v4, 16, v4
	v_and_b32_e32 v13, 0xffff, v5
	v_lshrrev_b32_e32 v5, 16, v5
	v_and_b32_e32 v16, 0xffff, v6
	v_lshrrev_b32_e32 v6, 16, v6
	v_and_b32_e32 v17, 0xffff, v7
	v_lshrrev_b32_e32 v7, 16, v7
	s_waitcnt vmcnt(4)
	v_and_b32_e32 v20, 0xffff, v8
	v_lshrrev_b32_e32 v8, 16, v8
	v_and_b32_e32 v21, 0xffff, v9
	v_lshrrev_b32_e32 v9, 16, v9
	v_and_b32_e32 v22, 0xffff, v10
	v_lshrrev_b32_e32 v10, 16, v10
	v_and_b32_e32 v23, 0xffff, v11
	v_lshrrev_b32_e32 v11, 16, v11
	v_lshl_add_u32 v211, v12, 6, v222
	v_lshl_add_u32 v12, v12, 7, v128
	buffer_load_dwordx4 v[122:125], v12, s[48:51], 0 offen
	buffer_load_dwordx2 v[126:127], v211, s[48:51], 0 offen
	v_lshl_add_u32 v211, v4, 6, v222
	v_lshl_add_u32 v4, v4, 7, v128
	buffer_load_dwordx4 v[32:35], v4, s[48:51], 0 offen
	buffer_load_dwordx2 v[36:37], v211, s[48:51], 0 offen
	v_lshl_add_u32 v211, v13, 6, v222
	v_lshl_add_u32 v13, v13, 7, v128
	buffer_load_dwordx4 v[116:119], v13, s[48:51], 0 offen
	buffer_load_dwordx2 v[120:121], v211, s[48:51], 0 offen
	v_lshl_add_u32 v211, v5, 6, v222
	v_lshl_add_u32 v5, v5, 7, v128
	buffer_load_dwordx4 v[38:41], v5, s[48:51], 0 offen
	buffer_load_dwordx2 v[42:43], v211, s[48:51], 0 offen
	v_lshl_add_u32 v211, v16, 6, v222
	v_lshl_add_u32 v16, v16, 7, v128
	buffer_load_dwordx4 v[110:113], v16, s[48:51], 0 offen
	buffer_load_dwordx2 v[114:115], v211, s[48:51], 0 offen
	v_lshl_add_u32 v211, v6, 6, v222
	v_lshl_add_u32 v6, v6, 7, v128
	buffer_load_dwordx4 v[44:47], v6, s[48:51], 0 offen
	buffer_load_dwordx2 v[48:49], v211, s[48:51], 0 offen
	v_lshl_add_u32 v211, v17, 6, v222
	v_lshl_add_u32 v17, v17, 7, v128
	buffer_load_dwordx4 v[104:107], v17, s[48:51], 0 offen
	buffer_load_dwordx2 v[108:109], v211, s[48:51], 0 offen
	v_lshl_add_u32 v211, v7, 6, v222
	v_lshl_add_u32 v7, v7, 7, v128
	buffer_load_dwordx4 v[50:53], v7, s[48:51], 0 offen
	buffer_load_dwordx2 v[54:55], v211, s[48:51], 0 offen
	v_lshl_add_u32 v211, v20, 6, v222
	v_lshl_add_u32 v20, v20, 7, v128
	buffer_load_dwordx4 v[98:101], v20, s[48:51], 0 offen
	buffer_load_dwordx2 v[102:103], v211, s[48:51], 0 offen
	v_lshl_add_u32 v211, v8, 6, v222
	v_lshl_add_u32 v8, v8, 7, v128
	buffer_load_dwordx4 v[56:59], v8, s[48:51], 0 offen
	buffer_load_dwordx2 v[60:61], v211, s[48:51], 0 offen
	v_lshl_add_u32 v211, v21, 6, v222
	v_lshl_add_u32 v21, v21, 7, v128
	buffer_load_dwordx4 v[92:95], v21, s[48:51], 0 offen
	buffer_load_dwordx2 v[96:97], v211, s[48:51], 0 offen
	v_lshl_add_u32 v211, v9, 6, v222
	v_lshl_add_u32 v9, v9, 7, v128
	buffer_load_dwordx4 v[62:65], v9, s[48:51], 0 offen
	buffer_load_dwordx2 v[66:67], v211, s[48:51], 0 offen
	v_lshl_add_u32 v211, v22, 6, v222
	v_lshl_add_u32 v22, v22, 7, v128
	buffer_load_dwordx4 v[86:89], v22, s[48:51], 0 offen
	buffer_load_dwordx2 v[90:91], v211, s[48:51], 0 offen
	v_lshl_add_u32 v211, v10, 6, v222
	v_lshl_add_u32 v10, v10, 7, v128
	buffer_load_dwordx4 v[68:71], v10, s[48:51], 0 offen
	buffer_load_dwordx2 v[72:73], v211, s[48:51], 0 offen
	v_lshl_add_u32 v211, v23, 6, v222
	v_lshl_add_u32 v23, v23, 7, v128
	buffer_load_dwordx4 v[80:83], v23, s[48:51], 0 offen
	buffer_load_dwordx2 v[84:85], v211, s[48:51], 0 offen
	v_lshl_add_u32 v211, v11, 6, v222
	v_lshl_add_u32 v11, v11, 7, v128
	buffer_load_dwordx4 v[74:77], v11, s[48:51], 0 offen
	buffer_load_dwordx2 v[78:79], v211, s[48:51], 0 offen
	v_cndmask_b32_e64 v4, v0, v19, s[0:1]
	v_ashrrev_i32_e32 v5, 31, v4
	v_lshlrev_b64 v[4:5], 8, v[4:5]
	v_lshl_add_u64 v[4:5], s[8:9], 0, v[4:5]
	v_lshl_add_u64 v[4:5], v[4:5], 0, v[14:15]
	global_load_dwordx4 v[158:161], v[4:5], off offset:16
	global_load_dwordx4 v[186:189], v[4:5], off
	v_lshlrev_b32_e32 v4, 5, v3
	v_lshlrev_b32_e32 v5, 2, v18
	v_and_b32_e32 v6, 0xffffff00, v2
	v_or3_b32 v216, v4, v5, v6
	v_or3_b32 v4, v6, v4, v5
	v_lshlrev_b64 v[2:3], 13, v[0:1]
	v_ashrrev_i32_e32 v5, 31, v4
	v_lshl_add_u64 v[2:3], v[4:5], 2, v[2:3]
	v_lshl_add_u64 v[2:3], s[4:5], 0, v[2:3]
	s_mov_b64 s[0:1], 0xcc00000
	v_ashrrev_i32_e32 v217, 31, v216
	v_lshl_add_u64 v[220:221], v[2:3], 0, s[0:1]
	s_lshl_b64 s[8:9], s[2:3], 13
	s_lshl_b32 s3, s2, 1
	s_waitcnt vmcnt(0) expcnt(0) lgkmcnt(0)
; DI void eseg_load(ESeg& r, __amdgpu_buffer_rsrc_t rs, int voff) { r.a = __builtin_amdgcn_raw_buffer_load_b128(rs, voff, 0, 0); r.b = __builtin_amdgcn_raw_buffer_load_b64(rs, voff + 16, 0, 0); }
; DI v32f eseg_unpack(const ESeg& r) { return __builtin_amdgcn_cvt_scalef32_pk32_f32_fp6((v6i){(int)r.a.x, (int)r.a.y, (int)r.a.z, (int)r.a.w, (int)r.b.x, (int)r.b.y}, 1.0f); }
; DI int id_of(const u32x4 (&d)[2], int r, unsigned mask = 0xffffu) { const unsigned w = d[r >> 3][(r >> 1) & 3]; return (r & 1) ? (int)((w >> 16) & mask) : (int)(w & mask); }
;     ...
;     for (;;) {
;         const int tn = t + nwx, tnn = tn + nwx, tn_c = tn < nrows ? tn : t, tnn_c = tnn < nrows ? tnn : t;
;         ids_load(idnn, RI16, tnn_c, g);
;         float wt[16];
; #pragma unroll
;         for (int q = 0; q < 4; ++q) { wt[q * 4] = wq[q].x; wt[q * 4 + 1] = wq[q].y; wt[q * 4 + 2] = wq[q].z; wt[q * 4 + 3] = wq[q].w; }
; #pragma unroll
;         for (int q = 0; q < 16; ++q) asm volatile("" : "+v"(wt[q]));
;         __builtin_amdgcn_sched_barrier(0);
; #pragma unroll
;         for (int q = 0; q < 4; ++q) wq[q] = *(const f32x4*)(Wg + (size_t)tn_c * 128 + q * 4);
;         float* xp = F.X + (size_t)t * D + col;
;         const f32x4 x1 = *(const f32x4*)xp, g2 = *(const f32x4*)(F.mod + ((size_t)l * 9 + modrow(t)) * MODW + 5 * D + col);
;         __builtin_amdgcn_sched_barrier(0);
;         f32x2 fa[16];
; #pragma unroll
;         for (int j = 0; j < 16; ++j) fa[j] = (f32x2){0.f, 0.f};
; #pragma unroll
;         for (int r = 0; r < 16; ++r) {
;             const v32f rr = eseg_unpack(rw[r]); const f32x2 w2 = {wt[r], wt[r]};
; #pragma unroll
;             for (int j = 0; j < 16; ++j) fa[j] = __builtin_elementwise_fma((f32x2){rr[2 * j], rr[2 * j + 1]}, w2, fa[j]);
;             eseg_load(rw[r], VS, id_of(idn, r, mask) * ESEG + s24);
;             if (r & 1) __builtin_amdgcn_sched_barrier(0);
;         }
.LBB0_1095:
	v_add_u32_e32 v1, s3, v0
	v_cmp_gt_i32_e64 s[0:1], s15, v1
	v_add_u32_e32 v250, s2, v0
	v_cmp_le_i32_e64 s[36:37], s15, v250
	v_cndmask_b32_e64 v2, v0, v1, s[0:1]
	v_ashrrev_i32_e32 v3, 31, v2
	v_lshlrev_b64 v[2:3], 8, v[2:3]
	v_lshl_add_u64 v[2:3], v[218:219], 0, v[2:3]
	global_load_dwordx4 v[130:133], v[2:3], off offset:16
	global_load_dwordx4 v[134:137], v[2:3], off
	v_cmp_gt_i32_e64 s[0:1], s15, v250
	s_nop 1
	v_cndmask_b32_e64 v2, v0, v250, s[0:1]
	v_ashrrev_i32_e32 v1, 31, v0
	v_lshrrev_b32_e32 v1, 21, v1
	v_add_u32_e32 v1, v0, v1
	v_ashrrev_i32_e32 v1, 11, v1
	v_cmp_gt_i32_e64 s[0:1], s13, v0
	v_ashrrev_i32_e32 v3, 31, v2
	v_lshlrev_b64 v[2:3], 9, v[2:3]
	v_cndmask_b32_e64 v0, 8, v1, s[0:1]
	s_mul_i32 s0, s92, 9
	v_add_u32_e32 v0, s0, v0
	v_lshl_add_u64 v[2:3], v[214:215], 0, v[2:3]
	v_mul_hi_i32_i24_e32 v1, 0xc000, v0
	v_mul_i32_i24_e32 v0, 0xc000, v0
	global_load_dwordx4 v[138:141], v[2:3], off offset:48
	global_load_dwordx4 v[142:145], v[2:3], off offset:32
	global_load_dwordx4 v[146:149], v[2:3], off offset:16
	global_load_dwordx4 v[150:153], v[2:3], off
	global_load_dwordx4 v[166:169], v[220:221], off
	v_lshl_add_u64 v[0:1], s[4:5], 0, v[0:1]
	v_lshl_add_u64 v[0:1], v[216:217], 2, v[0:1]
	s_mov_b32 s0, 0x10a000
	v_add_co_u32_e64 v0, s[0:1], s0, v0
	s_nop 1
	v_addc_co_u32_e64 v1, s[0:1], 0, v1, s[0:1]
	global_load_dwordx4 v[170:173], v[0:1], off
	s_waitcnt vmcnt(39)
	v_cvt_scalef32_pk32_f32_fp6 v[0:31], v[122:127], 1.0
	v_and_b32_e32 v210, 0xffff, v186
	v_lshl_add_u32 v211, v210, 6, v222
	v_lshl_add_u32 v210, v210, 7, v128
	v_pk_fma_f32 v[194:195], v[0:1], v[178:179], 0 op_sel_hi:[1,0,0]
	v_pk_fma_f32 v[196:197], v[2:3], v[178:179], 0 op_sel_hi:[1,0,0]
	v_pk_fma_f32 v[198:199], v[4:5], v[178:179], 0 op_sel_hi:[1,0,0]
	v_pk_fma_f32 v[200:201], v[6:7], v[178:179], 0 op_sel_hi:[1,0,0]
	v_pk_fma_f32 v[202:203], v[8:9], v[178:179], 0 op_sel_hi:[1,0,0]
	v_pk_fma_f32 v[204:205], v[10:11], v[178:179], 0 op_sel_hi:[1,0,0]
	v_pk_fma_f32 v[224:225], v[12:13], v[178:179], 0 op_sel_hi:[1,0,0]
	v_pk_fma_f32 v[226:227], v[14:15], v[178:179], 0 op_sel_hi:[1,0,0]
	v_pk_fma_f32 v[228:229], v[16:17], v[178:179], 0 op_sel_hi:[1,0,0]
	v_pk_fma_f32 v[230:231], v[18:19], v[178:179], 0 op_sel_hi:[1,0,0]
	v_pk_fma_f32 v[232:233], v[20:21], v[178:179], 0 op_sel_hi:[1,0,0]
	v_pk_fma_f32 v[234:235], v[22:23], v[178:179], 0 op_sel_hi:[1,0,0]
	v_pk_fma_f32 v[236:237], v[24:25], v[178:179], 0 op_sel_hi:[1,0,0]
	v_pk_fma_f32 v[182:183], v[26:27], v[178:179], 0 op_sel_hi:[1,0,0]
	v_pk_fma_f32 v[184:185], v[28:29], v[178:179], 0 op_sel_hi:[1,0,0]
	v_pk_fma_f32 v[208:209], v[30:31], v[178:179], 0 op_sel_hi:[1,0,0]
	buffer_load_dwordx4 v[122:125], v210, s[48:51], 0 offen
	buffer_load_dwordx2 v[126:127], v211, s[48:51], 0 offen
	s_waitcnt vmcnt(39)
	v_cvt_scalef32_pk32_f32_fp6 v[0:31], v[32:37], 1.0
	v_lshrrev_b32_e32 v210, 16, v186
	v_lshl_add_u32 v211, v210, 6, v222
	v_lshl_add_u32 v210, v210, 7, v128
	v_pk_fma_f32 v[194:195], v[0:1], v[178:179], v[194:195] op_sel:[0,1,0] op_sel_hi:[1,1,1]
	v_pk_fma_f32 v[196:197], v[2:3], v[178:179], v[196:197] op_sel:[0,1,0] op_sel_hi:[1,1,1]
	v_pk_fma_f32 v[198:199], v[4:5], v[178:179], v[198:199] op_sel:[0,1,0] op_sel_hi:[1,1,1]
	v_pk_fma_f32 v[200:201], v[6:7], v[178:179], v[200:201] op_sel:[0,1,0] op_sel_hi:[1,1,1]
	v_pk_fma_f32 v[202:203], v[8:9], v[178:179], v[202:203] op_sel:[0,1,0] op_sel_hi:[1,1,1]
	v_pk_fma_f32 v[204:205], v[10:11], v[178:179], v[204:205] op_sel:[0,1,0] op_sel_hi:[1,1,1]
	v_pk_fma_f32 v[224:225], v[12:13], v[178:179], v[224:225] op_sel:[0,1,0] op_sel_hi:[1,1,1]
	v_pk_fma_f32 v[226:227], v[14:15], v[178:179], v[226:227] op_sel:[0,1,0] op_sel_hi:[1,1,1]
	v_pk_fma_f32 v[228:229], v[16:17], v[178:179], v[228:229] op_sel:[0,1,0] op_sel_hi:[1,1,1]
	v_pk_fma_f32 v[230:231], v[18:19], v[178:179], v[230:231] op_sel:[0,1,0] op_sel_hi:[1,1,1]
	v_pk_fma_f32 v[232:233], v[20:21], v[178:179], v[232:233] op_sel:[0,1,0] op_sel_hi:[1,1,1]
	v_pk_fma_f32 v[234:235], v[22:23], v[178:179], v[234:235] op_sel:[0,1,0] op_sel_hi:[1,1,1]
	v_pk_fma_f32 v[236:237], v[24:25], v[178:179], v[236:237] op_sel:[0,1,0] op_sel_hi:[1,1,1]
	v_pk_fma_f32 v[182:183], v[26:27], v[178:179], v[182:183] op_sel:[0,1,0] op_sel_hi:[1,1,1]
	v_pk_fma_f32 v[184:185], v[28:29], v[178:179], v[184:185] op_sel:[0,1,0] op_sel_hi:[1,1,1]
	v_pk_fma_f32 v[208:209], v[30:31], v[178:179], v[208:209] op_sel:[0,1,0] op_sel_hi:[1,1,1]
	buffer_load_dwordx4 v[32:35], v210, s[48:51], 0 offen
	buffer_load_dwordx2 v[36:37], v211, s[48:51], 0 offen
	s_waitcnt vmcnt(39)
	v_cvt_scalef32_pk32_f32_fp6 v[0:31], v[116:121], 1.0
	v_and_b32_e32 v210, 0xffff, v187
	v_lshl_add_u32 v211, v210, 6, v222
	v_lshl_add_u32 v210, v210, 7, v128
	v_pk_fma_f32 v[194:195], v[0:1], v[180:181], v[194:195] op_sel_hi:[1,0,1]
	v_pk_fma_f32 v[196:197], v[2:3], v[180:181], v[196:197] op_sel_hi:[1,0,1]
	v_pk_fma_f32 v[198:199], v[4:5], v[180:181], v[198:199] op_sel_hi:[1,0,1]
	v_pk_fma_f32 v[200:201], v[6:7], v[180:181], v[200:201] op_sel_hi:[1,0,1]
	v_pk_fma_f32 v[202:203], v[8:9], v[180:181], v[202:203] op_sel_hi:[1,0,1]
	v_pk_fma_f32 v[204:205], v[10:11], v[180:181], v[204:205] op_sel_hi:[1,0,1]
	v_pk_fma_f32 v[224:225], v[12:13], v[180:181], v[224:225] op_sel_hi:[1,0,1]
	v_pk_fma_f32 v[226:227], v[14:15], v[180:181], v[226:227] op_sel_hi:[1,0,1]
	v_pk_fma_f32 v[228:229], v[16:17], v[180:181], v[228:229] op_sel_hi:[1,0,1]
	v_pk_fma_f32 v[230:231], v[18:19], v[180:181], v[230:231] op_sel_hi:[1,0,1]
	v_pk_fma_f32 v[232:233], v[20:21], v[180:181], v[232:233] op_sel_hi:[1,0,1]
	v_pk_fma_f32 v[234:235], v[22:23], v[180:181], v[234:235] op_sel_hi:[1,0,1]
	v_pk_fma_f32 v[236:237], v[24:25], v[180:181], v[236:237] op_sel_hi:[1,0,1]
	v_pk_fma_f32 v[182:183], v[26:27], v[180:181], v[182:183] op_sel_hi:[1,0,1]
	v_pk_fma_f32 v[184:185], v[28:29], v[180:181], v[184:185] op_sel_hi:[1,0,1]
	v_pk_fma_f32 v[208:209], v[30:31], v[180:181], v[208:209] op_sel_hi:[1,0,1]
	buffer_load_dwordx4 v[116:119], v210, s[48:51], 0 offen
	buffer_load_dwordx2 v[120:121], v211, s[48:51], 0 offen
	s_waitcnt vmcnt(39)
; DI void eseg_load(ESeg& r, __amdgpu_buffer_rsrc_t rs, int voff) { r.a = __builtin_amdgcn_raw_buffer_load_b128(rs, voff, 0, 0); r.b = __builtin_amdgcn_raw_buffer_load_b64(rs, voff + 16, 0, 0); }
; DI v32f eseg_unpack(const ESeg& r) { return __builtin_amdgcn_cvt_scalef32_pk32_f32_fp6((v6i){(int)r.a.x, (int)r.a.y, (int)r.a.z, (int)r.a.w, (int)r.b.x, (int)r.b.y}, 1.0f); }
; DI int id_of(const u32x4 (&d)[2], int r, unsigned mask = 0xffffu) { const unsigned w = d[r >> 3][(r >> 1) & 3]; return (r & 1) ? (int)((w >> 16) & mask) : (int)(w & mask); }
;     ...
; #pragma unroll
;         for (int r = 0; r < 16; ++r) {
;             const v32f rr = eseg_unpack(rw[r]); const f32x2 w2 = {wt[r], wt[r]};
; #pragma unroll
;             for (int j = 0; j < 16; ++j) fa[j] = __builtin_elementwise_fma((f32x2){rr[2 * j], rr[2 * j + 1]}, w2, fa[j]);
;             eseg_load(rw[r], VS, id_of(idn, r, mask) * ESEG + s24);
;             if (r & 1) __builtin_amdgcn_sched_barrier(0);
;         }
	v_cvt_scalef32_pk32_f32_fp6 v[0:31], v[38:43], 1.0
	v_lshrrev_b32_e32 v210, 16, v187
	v_lshl_add_u32 v211, v210, 6, v222
	v_lshl_add_u32 v210, v210, 7, v128
	v_pk_fma_f32 v[194:195], v[0:1], v[180:181], v[194:195] op_sel:[0,1,0] op_sel_hi:[1,1,1]
	v_pk_fma_f32 v[196:197], v[2:3], v[180:181], v[196:197] op_sel:[0,1,0] op_sel_hi:[1,1,1]
	v_pk_fma_f32 v[198:199], v[4:5], v[180:181], v[198:199] op_sel:[0,1,0] op_sel_hi:[1,1,1]
	v_pk_fma_f32 v[200:201], v[6:7], v[180:181], v[200:201] op_sel:[0,1,0] op_sel_hi:[1,1,1]
	v_pk_fma_f32 v[202:203], v[8:9], v[180:181], v[202:203] op_sel:[0,1,0] op_sel_hi:[1,1,1]
	v_pk_fma_f32 v[204:205], v[10:11], v[180:181], v[204:205] op_sel:[0,1,0] op_sel_hi:[1,1,1]
	v_pk_fma_f32 v[224:225], v[12:13], v[180:181], v[224:225] op_sel:[0,1,0] op_sel_hi:[1,1,1]
	v_pk_fma_f32 v[226:227], v[14:15], v[180:181], v[226:227] op_sel:[0,1,0] op_sel_hi:[1,1,1]
	v_pk_fma_f32 v[228:229], v[16:17], v[180:181], v[228:229] op_sel:[0,1,0] op_sel_hi:[1,1,1]
	v_pk_fma_f32 v[230:231], v[18:19], v[180:181], v[230:231] op_sel:[0,1,0] op_sel_hi:[1,1,1]
	v_pk_fma_f32 v[232:233], v[20:21], v[180:181], v[232:233] op_sel:[0,1,0] op_sel_hi:[1,1,1]
	v_pk_fma_f32 v[234:235], v[22:23], v[180:181], v[234:235] op_sel:[0,1,0] op_sel_hi:[1,1,1]
	v_pk_fma_f32 v[236:237], v[24:25], v[180:181], v[236:237] op_sel:[0,1,0] op_sel_hi:[1,1,1]
	v_pk_fma_f32 v[182:183], v[26:27], v[180:181], v[182:183] op_sel:[0,1,0] op_sel_hi:[1,1,1]
	v_pk_fma_f32 v[184:185], v[28:29], v[180:181], v[184:185] op_sel:[0,1,0] op_sel_hi:[1,1,1]
	v_pk_fma_f32 v[208:209], v[30:31], v[180:181], v[208:209] op_sel:[0,1,0] op_sel_hi:[1,1,1]
	buffer_load_dwordx4 v[38:41], v210, s[48:51], 0 offen
	buffer_load_dwordx2 v[42:43], v211, s[48:51], 0 offen
	s_waitcnt vmcnt(39)
	v_cvt_scalef32_pk32_f32_fp6 v[0:31], v[110:115], 1.0
	v_and_b32_e32 v210, 0xffff, v188
	v_lshl_add_u32 v211, v210, 6, v222
	v_lshl_add_u32 v210, v210, 7, v128
	v_pk_fma_f32 v[194:195], v[0:1], v[190:191], v[194:195] op_sel_hi:[1,0,1]
	v_pk_fma_f32 v[196:197], v[2:3], v[190:191], v[196:197] op_sel_hi:[1,0,1]
	v_pk_fma_f32 v[198:199], v[4:5], v[190:191], v[198:199] op_sel_hi:[1,0,1]
	v_pk_fma_f32 v[200:201], v[6:7], v[190:191], v[200:201] op_sel_hi:[1,0,1]
	v_pk_fma_f32 v[202:203], v[8:9], v[190:191], v[202:203] op_sel_hi:[1,0,1]
	v_pk_fma_f32 v[204:205], v[10:11], v[190:191], v[204:205] op_sel_hi:[1,0,1]
	v_pk_fma_f32 v[224:225], v[12:13], v[190:191], v[224:225] op_sel_hi:[1,0,1]
	v_pk_fma_f32 v[226:227], v[14:15], v[190:191], v[226:227] op_sel_hi:[1,0,1]
	v_pk_fma_f32 v[228:229], v[16:17], v[190:191], v[228:229] op_sel_hi:[1,0,1]
	v_pk_fma_f32 v[230:231], v[18:19], v[190:191], v[230:231] op_sel_hi:[1,0,1]
	v_pk_fma_f32 v[232:233], v[20:21], v[190:191], v[232:233] op_sel_hi:[1,0,1]
	v_pk_fma_f32 v[234:235], v[22:23], v[190:191], v[234:235] op_sel_hi:[1,0,1]
	v_pk_fma_f32 v[236:237], v[24:25], v[190:191], v[236:237] op_sel_hi:[1,0,1]
	v_pk_fma_f32 v[182:183], v[26:27], v[190:191], v[182:183] op_sel_hi:[1,0,1]
	v_pk_fma_f32 v[184:185], v[28:29], v[190:191], v[184:185] op_sel_hi:[1,0,1]
	v_pk_fma_f32 v[208:209], v[30:31], v[190:191], v[208:209] op_sel_hi:[1,0,1]
	buffer_load_dwordx4 v[110:113], v210, s[48:51], 0 offen
	buffer_load_dwordx2 v[114:115], v211, s[48:51], 0 offen
	s_waitcnt vmcnt(39)
	v_cvt_scalef32_pk32_f32_fp6 v[0:31], v[44:49], 1.0
	v_lshrrev_b32_e32 v210, 16, v188
	v_lshl_add_u32 v211, v210, 6, v222
	v_lshl_add_u32 v210, v210, 7, v128
	v_pk_fma_f32 v[194:195], v[0:1], v[190:191], v[194:195] op_sel:[0,1,0] op_sel_hi:[1,1,1]
	v_pk_fma_f32 v[196:197], v[2:3], v[190:191], v[196:197] op_sel:[0,1,0] op_sel_hi:[1,1,1]
	v_pk_fma_f32 v[198:199], v[4:5], v[190:191], v[198:199] op_sel:[0,1,0] op_sel_hi:[1,1,1]
	v_pk_fma_f32 v[200:201], v[6:7], v[190:191], v[200:201] op_sel:[0,1,0] op_sel_hi:[1,1,1]
	v_pk_fma_f32 v[202:203], v[8:9], v[190:191], v[202:203] op_sel:[0,1,0] op_sel_hi:[1,1,1]
	v_pk_fma_f32 v[204:205], v[10:11], v[190:191], v[204:205] op_sel:[0,1,0] op_sel_hi:[1,1,1]
	v_pk_fma_f32 v[224:225], v[12:13], v[190:191], v[224:225] op_sel:[0,1,0] op_sel_hi:[1,1,1]
	v_pk_fma_f32 v[226:227], v[14:15], v[190:191], v[226:227] op_sel:[0,1,0] op_sel_hi:[1,1,1]
	v_pk_fma_f32 v[228:229], v[16:17], v[190:191], v[228:229] op_sel:[0,1,0] op_sel_hi:[1,1,1]
	v_pk_fma_f32 v[230:231], v[18:19], v[190:191], v[230:231] op_sel:[0,1,0] op_sel_hi:[1,1,1]
	v_pk_fma_f32 v[232:233], v[20:21], v[190:191], v[232:233] op_sel:[0,1,0] op_sel_hi:[1,1,1]
	v_pk_fma_f32 v[234:235], v[22:23], v[190:191], v[234:235] op_sel:[0,1,0] op_sel_hi:[1,1,1]
	v_pk_fma_f32 v[236:237], v[24:25], v[190:191], v[236:237] op_sel:[0,1,0] op_sel_hi:[1,1,1]
	v_pk_fma_f32 v[182:183], v[26:27], v[190:191], v[182:183] op_sel:[0,1,0] op_sel_hi:[1,1,1]
	v_pk_fma_f32 v[184:185], v[28:29], v[190:191], v[184:185] op_sel:[0,1,0] op_sel_hi:[1,1,1]
	v_pk_fma_f32 v[208:209], v[30:31], v[190:191], v[208:209] op_sel:[0,1,0] op_sel_hi:[1,1,1]
	buffer_load_dwordx4 v[44:47], v210, s[48:51], 0 offen
	buffer_load_dwordx2 v[48:49], v211, s[48:51], 0 offen
	s_waitcnt vmcnt(39)
; DI void eseg_load(ESeg& r, __amdgpu_buffer_rsrc_t rs, int voff) { r.a = __builtin_amdgcn_raw_buffer_load_b128(rs, voff, 0, 0); r.b = __builtin_amdgcn_raw_buffer_load_b64(rs, voff + 16, 0, 0); }
; DI v32f eseg_unpack(const ESeg& r) { return __builtin_amdgcn_cvt_scalef32_pk32_f32_fp6((v6i){(int)r.a.x, (int)r.a.y, (int)r.a.z, (int)r.a.w, (int)r.b.x, (int)r.b.y}, 1.0f); }
; DI int id_of(const u32x4 (&d)[2], int r, unsigned mask = 0xffffu) { const unsigned w = d[r >> 3][(r >> 1) & 3]; return (r & 1) ? (int)((w >> 16) & mask) : (int)(w & mask); }
;     ...
; #pragma unroll
;         for (int r = 0; r < 16; ++r) {
;             const v32f rr = eseg_unpack(rw[r]); const f32x2 w2 = {wt[r], wt[r]};
; #pragma unroll
;             for (int j = 0; j < 16; ++j) fa[j] = __builtin_elementwise_fma((f32x2){rr[2 * j], rr[2 * j + 1]}, w2, fa[j]);
;             eseg_load(rw[r], VS, id_of(idn, r, mask) * ESEG + s24);
;             if (r & 1) __builtin_amdgcn_sched_barrier(0);
;         }
	v_cvt_scalef32_pk32_f32_fp6 v[0:31], v[104:109], 1.0
	v_and_b32_e32 v210, 0xffff, v189
	v_lshl_add_u32 v211, v210, 6, v222
	v_lshl_add_u32 v210, v210, 7, v128
	v_pk_fma_f32 v[194:195], v[0:1], v[192:193], v[194:195] op_sel_hi:[1,0,1]
	v_pk_fma_f32 v[196:197], v[2:3], v[192:193], v[196:197] op_sel_hi:[1,0,1]
	v_pk_fma_f32 v[198:199], v[4:5], v[192:193], v[198:199] op_sel_hi:[1,0,1]
	v_pk_fma_f32 v[200:201], v[6:7], v[192:193], v[200:201] op_sel_hi:[1,0,1]
	v_pk_fma_f32 v[202:203], v[8:9], v[192:193], v[202:203] op_sel_hi:[1,0,1]
	v_pk_fma_f32 v[204:205], v[10:11], v[192:193], v[204:205] op_sel_hi:[1,0,1]
	v_pk_fma_f32 v[224:225], v[12:13], v[192:193], v[224:225] op_sel_hi:[1,0,1]
	v_pk_fma_f32 v[226:227], v[14:15], v[192:193], v[226:227] op_sel_hi:[1,0,1]
	v_pk_fma_f32 v[228:229], v[16:17], v[192:193], v[228:229] op_sel_hi:[1,0,1]
	v_pk_fma_f32 v[230:231], v[18:19], v[192:193], v[230:231] op_sel_hi:[1,0,1]
	v_pk_fma_f32 v[232:233], v[20:21], v[192:193], v[232:233] op_sel_hi:[1,0,1]
	v_pk_fma_f32 v[234:235], v[22:23], v[192:193], v[234:235] op_sel_hi:[1,0,1]
	v_pk_fma_f32 v[236:237], v[24:25], v[192:193], v[236:237] op_sel_hi:[1,0,1]
	v_pk_fma_f32 v[182:183], v[26:27], v[192:193], v[182:183] op_sel_hi:[1,0,1]
	v_pk_fma_f32 v[184:185], v[28:29], v[192:193], v[184:185] op_sel_hi:[1,0,1]
	v_pk_fma_f32 v[208:209], v[30:31], v[192:193], v[208:209] op_sel_hi:[1,0,1]
	buffer_load_dwordx4 v[104:107], v210, s[48:51], 0 offen
	buffer_load_dwordx2 v[108:109], v211, s[48:51], 0 offen
	s_waitcnt vmcnt(39)
	v_cvt_scalef32_pk32_f32_fp6 v[0:31], v[50:55], 1.0
	v_lshrrev_b32_e32 v210, 16, v189
	v_lshl_add_u32 v211, v210, 6, v222
	v_lshl_add_u32 v210, v210, 7, v128
	v_pk_fma_f32 v[194:195], v[0:1], v[192:193], v[194:195] op_sel:[0,1,0] op_sel_hi:[1,1,1]
	v_pk_fma_f32 v[196:197], v[2:3], v[192:193], v[196:197] op_sel:[0,1,0] op_sel_hi:[1,1,1]
	v_pk_fma_f32 v[198:199], v[4:5], v[192:193], v[198:199] op_sel:[0,1,0] op_sel_hi:[1,1,1]
	v_pk_fma_f32 v[200:201], v[6:7], v[192:193], v[200:201] op_sel:[0,1,0] op_sel_hi:[1,1,1]
	v_pk_fma_f32 v[202:203], v[8:9], v[192:193], v[202:203] op_sel:[0,1,0] op_sel_hi:[1,1,1]
	v_pk_fma_f32 v[204:205], v[10:11], v[192:193], v[204:205] op_sel:[0,1,0] op_sel_hi:[1,1,1]
	v_pk_fma_f32 v[224:225], v[12:13], v[192:193], v[224:225] op_sel:[0,1,0] op_sel_hi:[1,1,1]
	v_pk_fma_f32 v[226:227], v[14:15], v[192:193], v[226:227] op_sel:[0,1,0] op_sel_hi:[1,1,1]
	v_pk_fma_f32 v[228:229], v[16:17], v[192:193], v[228:229] op_sel:[0,1,0] op_sel_hi:[1,1,1]
	v_pk_fma_f32 v[230:231], v[18:19], v[192:193], v[230:231] op_sel:[0,1,0] op_sel_hi:[1,1,1]
	v_pk_fma_f32 v[232:233], v[20:21], v[192:193], v[232:233] op_sel:[0,1,0] op_sel_hi:[1,1,1]
	v_pk_fma_f32 v[234:235], v[22:23], v[192:193], v[234:235] op_sel:[0,1,0] op_sel_hi:[1,1,1]
	v_pk_fma_f32 v[236:237], v[24:25], v[192:193], v[236:237] op_sel:[0,1,0] op_sel_hi:[1,1,1]
	v_pk_fma_f32 v[182:183], v[26:27], v[192:193], v[182:183] op_sel:[0,1,0] op_sel_hi:[1,1,1]
	v_pk_fma_f32 v[184:185], v[28:29], v[192:193], v[184:185] op_sel:[0,1,0] op_sel_hi:[1,1,1]
	v_pk_fma_f32 v[208:209], v[30:31], v[192:193], v[208:209] op_sel:[0,1,0] op_sel_hi:[1,1,1]
	buffer_load_dwordx4 v[50:53], v210, s[48:51], 0 offen
	buffer_load_dwordx2 v[54:55], v211, s[48:51], 0 offen
	s_waitcnt vmcnt(39)
	v_cvt_scalef32_pk32_f32_fp6 v[0:31], v[98:103], 1.0
	v_and_b32_e32 v210, 0xffff, v158
	v_lshl_add_u32 v211, v210, 6, v222
	v_lshl_add_u32 v210, v210, 7, v128
	v_pk_fma_f32 v[194:195], v[0:1], v[174:175], v[194:195] op_sel_hi:[1,0,1]
	v_pk_fma_f32 v[196:197], v[2:3], v[174:175], v[196:197] op_sel_hi:[1,0,1]
	v_pk_fma_f32 v[198:199], v[4:5], v[174:175], v[198:199] op_sel_hi:[1,0,1]
	v_pk_fma_f32 v[200:201], v[6:7], v[174:175], v[200:201] op_sel_hi:[1,0,1]
	v_pk_fma_f32 v[202:203], v[8:9], v[174:175], v[202:203] op_sel_hi:[1,0,1]
	v_pk_fma_f32 v[204:205], v[10:11], v[174:175], v[204:205] op_sel_hi:[1,0,1]
	v_pk_fma_f32 v[224:225], v[12:13], v[174:175], v[224:225] op_sel_hi:[1,0,1]
	v_pk_fma_f32 v[226:227], v[14:15], v[174:175], v[226:227] op_sel_hi:[1,0,1]
	v_pk_fma_f32 v[228:229], v[16:17], v[174:175], v[228:229] op_sel_hi:[1,0,1]
	v_pk_fma_f32 v[230:231], v[18:19], v[174:175], v[230:231] op_sel_hi:[1,0,1]
	v_pk_fma_f32 v[232:233], v[20:21], v[174:175], v[232:233] op_sel_hi:[1,0,1]
	v_pk_fma_f32 v[234:235], v[22:23], v[174:175], v[234:235] op_sel_hi:[1,0,1]
	v_pk_fma_f32 v[236:237], v[24:25], v[174:175], v[236:237] op_sel_hi:[1,0,1]
	v_pk_fma_f32 v[182:183], v[26:27], v[174:175], v[182:183] op_sel_hi:[1,0,1]
	v_pk_fma_f32 v[184:185], v[28:29], v[174:175], v[184:185] op_sel_hi:[1,0,1]
	v_pk_fma_f32 v[208:209], v[30:31], v[174:175], v[208:209] op_sel_hi:[1,0,1]
	buffer_load_dwordx4 v[98:101], v210, s[48:51], 0 offen
	buffer_load_dwordx2 v[102:103], v211, s[48:51], 0 offen
	s_waitcnt vmcnt(39)
; DI void eseg_load(ESeg& r, __amdgpu_buffer_rsrc_t rs, int voff) { r.a = __builtin_amdgcn_raw_buffer_load_b128(rs, voff, 0, 0); r.b = __builtin_amdgcn_raw_buffer_load_b64(rs, voff + 16, 0, 0); }
; DI v32f eseg_unpack(const ESeg& r) { return __builtin_amdgcn_cvt_scalef32_pk32_f32_fp6((v6i){(int)r.a.x, (int)r.a.y, (int)r.a.z, (int)r.a.w, (int)r.b.x, (int)r.b.y}, 1.0f); }
; DI int id_of(const u32x4 (&d)[2], int r, unsigned mask = 0xffffu) { const unsigned w = d[r >> 3][(r >> 1) & 3]; return (r & 1) ? (int)((w >> 16) & mask) : (int)(w & mask); }
;     ...
; #pragma unroll
;         for (int r = 0; r < 16; ++r) {
;             const v32f rr = eseg_unpack(rw[r]); const f32x2 w2 = {wt[r], wt[r]};
; #pragma unroll
;             for (int j = 0; j < 16; ++j) fa[j] = __builtin_elementwise_fma((f32x2){rr[2 * j], rr[2 * j + 1]}, w2, fa[j]);
;             eseg_load(rw[r], VS, id_of(idn, r, mask) * ESEG + s24);
;             if (r & 1) __builtin_amdgcn_sched_barrier(0);
;         }
	v_cvt_scalef32_pk32_f32_fp6 v[0:31], v[56:61], 1.0
	v_lshrrev_b32_e32 v210, 16, v158
	v_lshl_add_u32 v211, v210, 6, v222
	v_lshl_add_u32 v210, v210, 7, v128
	v_pk_fma_f32 v[194:195], v[0:1], v[174:175], v[194:195] op_sel:[0,1,0] op_sel_hi:[1,1,1]
	v_pk_fma_f32 v[196:197], v[2:3], v[174:175], v[196:197] op_sel:[0,1,0] op_sel_hi:[1,1,1]
	v_pk_fma_f32 v[198:199], v[4:5], v[174:175], v[198:199] op_sel:[0,1,0] op_sel_hi:[1,1,1]
	v_pk_fma_f32 v[200:201], v[6:7], v[174:175], v[200:201] op_sel:[0,1,0] op_sel_hi:[1,1,1]
	v_pk_fma_f32 v[202:203], v[8:9], v[174:175], v[202:203] op_sel:[0,1,0] op_sel_hi:[1,1,1]
	v_pk_fma_f32 v[204:205], v[10:11], v[174:175], v[204:205] op_sel:[0,1,0] op_sel_hi:[1,1,1]
	v_pk_fma_f32 v[224:225], v[12:13], v[174:175], v[224:225] op_sel:[0,1,0] op_sel_hi:[1,1,1]
	v_pk_fma_f32 v[226:227], v[14:15], v[174:175], v[226:227] op_sel:[0,1,0] op_sel_hi:[1,1,1]
	v_pk_fma_f32 v[228:229], v[16:17], v[174:175], v[228:229] op_sel:[0,1,0] op_sel_hi:[1,1,1]
	v_pk_fma_f32 v[230:231], v[18:19], v[174:175], v[230:231] op_sel:[0,1,0] op_sel_hi:[1,1,1]
	v_pk_fma_f32 v[232:233], v[20:21], v[174:175], v[232:233] op_sel:[0,1,0] op_sel_hi:[1,1,1]
	v_pk_fma_f32 v[234:235], v[22:23], v[174:175], v[234:235] op_sel:[0,1,0] op_sel_hi:[1,1,1]
	v_pk_fma_f32 v[236:237], v[24:25], v[174:175], v[236:237] op_sel:[0,1,0] op_sel_hi:[1,1,1]
	v_pk_fma_f32 v[182:183], v[26:27], v[174:175], v[182:183] op_sel:[0,1,0] op_sel_hi:[1,1,1]
	v_pk_fma_f32 v[184:185], v[28:29], v[174:175], v[184:185] op_sel:[0,1,0] op_sel_hi:[1,1,1]
	v_pk_fma_f32 v[208:209], v[30:31], v[174:175], v[208:209] op_sel:[0,1,0] op_sel_hi:[1,1,1]
	buffer_load_dwordx4 v[56:59], v210, s[48:51], 0 offen
	buffer_load_dwordx2 v[60:61], v211, s[48:51], 0 offen
	s_waitcnt vmcnt(39)
	v_cvt_scalef32_pk32_f32_fp6 v[0:31], v[92:97], 1.0
	v_and_b32_e32 v210, 0xffff, v159
	v_lshl_add_u32 v211, v210, 6, v222
	v_lshl_add_u32 v210, v210, 7, v128
	v_pk_fma_f32 v[194:195], v[0:1], v[176:177], v[194:195] op_sel_hi:[1,0,1]
	v_pk_fma_f32 v[196:197], v[2:3], v[176:177], v[196:197] op_sel_hi:[1,0,1]
	v_pk_fma_f32 v[198:199], v[4:5], v[176:177], v[198:199] op_sel_hi:[1,0,1]
	v_pk_fma_f32 v[200:201], v[6:7], v[176:177], v[200:201] op_sel_hi:[1,0,1]
	v_pk_fma_f32 v[202:203], v[8:9], v[176:177], v[202:203] op_sel_hi:[1,0,1]
	v_pk_fma_f32 v[204:205], v[10:11], v[176:177], v[204:205] op_sel_hi:[1,0,1]
	v_pk_fma_f32 v[224:225], v[12:13], v[176:177], v[224:225] op_sel_hi:[1,0,1]
	v_pk_fma_f32 v[226:227], v[14:15], v[176:177], v[226:227] op_sel_hi:[1,0,1]
	v_pk_fma_f32 v[228:229], v[16:17], v[176:177], v[228:229] op_sel_hi:[1,0,1]
	v_pk_fma_f32 v[230:231], v[18:19], v[176:177], v[230:231] op_sel_hi:[1,0,1]
	v_pk_fma_f32 v[232:233], v[20:21], v[176:177], v[232:233] op_sel_hi:[1,0,1]
	v_pk_fma_f32 v[234:235], v[22:23], v[176:177], v[234:235] op_sel_hi:[1,0,1]
	v_pk_fma_f32 v[236:237], v[24:25], v[176:177], v[236:237] op_sel_hi:[1,0,1]
	v_pk_fma_f32 v[182:183], v[26:27], v[176:177], v[182:183] op_sel_hi:[1,0,1]
	v_pk_fma_f32 v[184:185], v[28:29], v[176:177], v[184:185] op_sel_hi:[1,0,1]
	v_pk_fma_f32 v[208:209], v[30:31], v[176:177], v[208:209] op_sel_hi:[1,0,1]
	buffer_load_dwordx4 v[92:95], v210, s[48:51], 0 offen
	buffer_load_dwordx2 v[96:97], v211, s[48:51], 0 offen
	s_waitcnt vmcnt(39)
	v_cvt_scalef32_pk32_f32_fp6 v[0:31], v[62:67], 1.0
	v_lshrrev_b32_e32 v210, 16, v159
	v_lshl_add_u32 v211, v210, 6, v222
	v_lshl_add_u32 v210, v210, 7, v128
	v_pk_fma_f32 v[194:195], v[0:1], v[176:177], v[194:195] op_sel:[0,1,0] op_sel_hi:[1,1,1]
	v_pk_fma_f32 v[196:197], v[2:3], v[176:177], v[196:197] op_sel:[0,1,0] op_sel_hi:[1,1,1]
	v_pk_fma_f32 v[198:199], v[4:5], v[176:177], v[198:199] op_sel:[0,1,0] op_sel_hi:[1,1,1]
	v_pk_fma_f32 v[200:201], v[6:7], v[176:177], v[200:201] op_sel:[0,1,0] op_sel_hi:[1,1,1]
	v_pk_fma_f32 v[202:203], v[8:9], v[176:177], v[202:203] op_sel:[0,1,0] op_sel_hi:[1,1,1]
	v_pk_fma_f32 v[204:205], v[10:11], v[176:177], v[204:205] op_sel:[0,1,0] op_sel_hi:[1,1,1]
	v_pk_fma_f32 v[224:225], v[12:13], v[176:177], v[224:225] op_sel:[0,1,0] op_sel_hi:[1,1,1]
	v_pk_fma_f32 v[226:227], v[14:15], v[176:177], v[226:227] op_sel:[0,1,0] op_sel_hi:[1,1,1]
	v_pk_fma_f32 v[228:229], v[16:17], v[176:177], v[228:229] op_sel:[0,1,0] op_sel_hi:[1,1,1]
	v_pk_fma_f32 v[230:231], v[18:19], v[176:177], v[230:231] op_sel:[0,1,0] op_sel_hi:[1,1,1]
	v_pk_fma_f32 v[232:233], v[20:21], v[176:177], v[232:233] op_sel:[0,1,0] op_sel_hi:[1,1,1]
	v_pk_fma_f32 v[234:235], v[22:23], v[176:177], v[234:235] op_sel:[0,1,0] op_sel_hi:[1,1,1]
	v_pk_fma_f32 v[236:237], v[24:25], v[176:177], v[236:237] op_sel:[0,1,0] op_sel_hi:[1,1,1]
	v_pk_fma_f32 v[182:183], v[26:27], v[176:177], v[182:183] op_sel:[0,1,0] op_sel_hi:[1,1,1]
	v_pk_fma_f32 v[184:185], v[28:29], v[176:177], v[184:185] op_sel:[0,1,0] op_sel_hi:[1,1,1]
	v_pk_fma_f32 v[208:209], v[30:31], v[176:177], v[208:209] op_sel:[0,1,0] op_sel_hi:[1,1,1]
	buffer_load_dwordx4 v[62:65], v210, s[48:51], 0 offen
	buffer_load_dwordx2 v[66:67], v211, s[48:51], 0 offen
	s_waitcnt vmcnt(39)
; DI void eseg_load(ESeg& r, __amdgpu_buffer_rsrc_t rs, int voff) { r.a = __builtin_amdgcn_raw_buffer_load_b128(rs, voff, 0, 0); r.b = __builtin_amdgcn_raw_buffer_load_b64(rs, voff + 16, 0, 0); }
; DI v32f eseg_unpack(const ESeg& r) { return __builtin_amdgcn_cvt_scalef32_pk32_f32_fp6((v6i){(int)r.a.x, (int)r.a.y, (int)r.a.z, (int)r.a.w, (int)r.b.x, (int)r.b.y}, 1.0f); }
; DI int id_of(const u32x4 (&d)[2], int r, unsigned mask = 0xffffu) { const unsigned w = d[r >> 3][(r >> 1) & 3]; return (r & 1) ? (int)((w >> 16) & mask) : (int)(w & mask); }
;     ...
; #pragma unroll
;         for (int r = 0; r < 16; ++r) {
;             const v32f rr = eseg_unpack(rw[r]); const f32x2 w2 = {wt[r], wt[r]};
; #pragma unroll
;             for (int j = 0; j < 16; ++j) fa[j] = __builtin_elementwise_fma((f32x2){rr[2 * j], rr[2 * j + 1]}, w2, fa[j]);
;             eseg_load(rw[r], VS, id_of(idn, r, mask) * ESEG + s24);
;             if (r & 1) __builtin_amdgcn_sched_barrier(0);
;         }
	v_cvt_scalef32_pk32_f32_fp6 v[0:31], v[86:91], 1.0
	v_and_b32_e32 v210, 0xffff, v160
	v_lshl_add_u32 v211, v210, 6, v222
	v_lshl_add_u32 v210, v210, 7, v128
	v_pk_fma_f32 v[194:195], v[0:1], v[162:163], v[194:195] op_sel_hi:[1,0,1]
	v_pk_fma_f32 v[196:197], v[2:3], v[162:163], v[196:197] op_sel_hi:[1,0,1]
	v_pk_fma_f32 v[198:199], v[4:5], v[162:163], v[198:199] op_sel_hi:[1,0,1]
	v_pk_fma_f32 v[200:201], v[6:7], v[162:163], v[200:201] op_sel_hi:[1,0,1]
	v_pk_fma_f32 v[202:203], v[8:9], v[162:163], v[202:203] op_sel_hi:[1,0,1]
	v_pk_fma_f32 v[204:205], v[10:11], v[162:163], v[204:205] op_sel_hi:[1,0,1]
	v_pk_fma_f32 v[224:225], v[12:13], v[162:163], v[224:225] op_sel_hi:[1,0,1]
	v_pk_fma_f32 v[226:227], v[14:15], v[162:163], v[226:227] op_sel_hi:[1,0,1]
	v_pk_fma_f32 v[228:229], v[16:17], v[162:163], v[228:229] op_sel_hi:[1,0,1]
	v_pk_fma_f32 v[230:231], v[18:19], v[162:163], v[230:231] op_sel_hi:[1,0,1]
	v_pk_fma_f32 v[232:233], v[20:21], v[162:163], v[232:233] op_sel_hi:[1,0,1]
	v_pk_fma_f32 v[234:235], v[22:23], v[162:163], v[234:235] op_sel_hi:[1,0,1]
	v_pk_fma_f32 v[236:237], v[24:25], v[162:163], v[236:237] op_sel_hi:[1,0,1]
	v_pk_fma_f32 v[182:183], v[26:27], v[162:163], v[182:183] op_sel_hi:[1,0,1]
	v_pk_fma_f32 v[184:185], v[28:29], v[162:163], v[184:185] op_sel_hi:[1,0,1]
	v_pk_fma_f32 v[208:209], v[30:31], v[162:163], v[208:209] op_sel_hi:[1,0,1]
	buffer_load_dwordx4 v[86:89], v210, s[48:51], 0 offen
	buffer_load_dwordx2 v[90:91], v211, s[48:51], 0 offen
	s_waitcnt vmcnt(39)
	v_cvt_scalef32_pk32_f32_fp6 v[0:31], v[68:73], 1.0
	v_lshrrev_b32_e32 v210, 16, v160
	v_lshl_add_u32 v211, v210, 6, v222
	v_lshl_add_u32 v210, v210, 7, v128
	v_pk_fma_f32 v[194:195], v[0:1], v[162:163], v[194:195] op_sel:[0,1,0] op_sel_hi:[1,1,1]
	v_pk_fma_f32 v[196:197], v[2:3], v[162:163], v[196:197] op_sel:[0,1,0] op_sel_hi:[1,1,1]
	v_pk_fma_f32 v[198:199], v[4:5], v[162:163], v[198:199] op_sel:[0,1,0] op_sel_hi:[1,1,1]
	v_pk_fma_f32 v[200:201], v[6:7], v[162:163], v[200:201] op_sel:[0,1,0] op_sel_hi:[1,1,1]
	v_pk_fma_f32 v[202:203], v[8:9], v[162:163], v[202:203] op_sel:[0,1,0] op_sel_hi:[1,1,1]
	v_pk_fma_f32 v[204:205], v[10:11], v[162:163], v[204:205] op_sel:[0,1,0] op_sel_hi:[1,1,1]
	v_pk_fma_f32 v[224:225], v[12:13], v[162:163], v[224:225] op_sel:[0,1,0] op_sel_hi:[1,1,1]
	v_pk_fma_f32 v[226:227], v[14:15], v[162:163], v[226:227] op_sel:[0,1,0] op_sel_hi:[1,1,1]
	v_pk_fma_f32 v[228:229], v[16:17], v[162:163], v[228:229] op_sel:[0,1,0] op_sel_hi:[1,1,1]
	v_pk_fma_f32 v[230:231], v[18:19], v[162:163], v[230:231] op_sel:[0,1,0] op_sel_hi:[1,1,1]
	v_pk_fma_f32 v[232:233], v[20:21], v[162:163], v[232:233] op_sel:[0,1,0] op_sel_hi:[1,1,1]
	v_pk_fma_f32 v[234:235], v[22:23], v[162:163], v[234:235] op_sel:[0,1,0] op_sel_hi:[1,1,1]
	v_pk_fma_f32 v[236:237], v[24:25], v[162:163], v[236:237] op_sel:[0,1,0] op_sel_hi:[1,1,1]
	v_pk_fma_f32 v[182:183], v[26:27], v[162:163], v[182:183] op_sel:[0,1,0] op_sel_hi:[1,1,1]
	v_pk_fma_f32 v[184:185], v[28:29], v[162:163], v[184:185] op_sel:[0,1,0] op_sel_hi:[1,1,1]
	v_pk_fma_f32 v[208:209], v[30:31], v[162:163], v[208:209] op_sel:[0,1,0] op_sel_hi:[1,1,1]
	buffer_load_dwordx4 v[68:71], v210, s[48:51], 0 offen
	buffer_load_dwordx2 v[72:73], v211, s[48:51], 0 offen
	s_waitcnt vmcnt(39)
	v_cvt_scalef32_pk32_f32_fp6 v[0:31], v[80:85], 1.0
	v_and_b32_e32 v210, 0xffff, v161
	v_lshl_add_u32 v211, v210, 6, v222
	v_lshl_add_u32 v210, v210, 7, v128
	v_pk_fma_f32 v[194:195], v[0:1], v[164:165], v[194:195] op_sel_hi:[1,0,1]
	v_pk_fma_f32 v[196:197], v[2:3], v[164:165], v[196:197] op_sel_hi:[1,0,1]
	v_pk_fma_f32 v[198:199], v[4:5], v[164:165], v[198:199] op_sel_hi:[1,0,1]
	v_pk_fma_f32 v[200:201], v[6:7], v[164:165], v[200:201] op_sel_hi:[1,0,1]
	v_pk_fma_f32 v[202:203], v[8:9], v[164:165], v[202:203] op_sel_hi:[1,0,1]
	v_pk_fma_f32 v[204:205], v[10:11], v[164:165], v[204:205] op_sel_hi:[1,0,1]
	v_pk_fma_f32 v[224:225], v[12:13], v[164:165], v[224:225] op_sel_hi:[1,0,1]
	v_pk_fma_f32 v[226:227], v[14:15], v[164:165], v[226:227] op_sel_hi:[1,0,1]
	v_pk_fma_f32 v[228:229], v[16:17], v[164:165], v[228:229] op_sel_hi:[1,0,1]
	v_pk_fma_f32 v[230:231], v[18:19], v[164:165], v[230:231] op_sel_hi:[1,0,1]
	v_pk_fma_f32 v[232:233], v[20:21], v[164:165], v[232:233] op_sel_hi:[1,0,1]
	v_pk_fma_f32 v[234:235], v[22:23], v[164:165], v[234:235] op_sel_hi:[1,0,1]
	v_pk_fma_f32 v[236:237], v[24:25], v[164:165], v[236:237] op_sel_hi:[1,0,1]
	v_pk_fma_f32 v[182:183], v[26:27], v[164:165], v[182:183] op_sel_hi:[1,0,1]
	v_pk_fma_f32 v[184:185], v[28:29], v[164:165], v[184:185] op_sel_hi:[1,0,1]
	v_pk_fma_f32 v[208:209], v[30:31], v[164:165], v[208:209] op_sel_hi:[1,0,1]
	buffer_load_dwordx4 v[80:83], v210, s[48:51], 0 offen
	buffer_load_dwordx2 v[84:85], v211, s[48:51], 0 offen
	s_waitcnt vmcnt(39)
; template <int CTRL> DI float dpp_add(float x) { return x + __uint_as_float(__builtin_amdgcn_update_dpp(0u, __float_as_uint(x), CTRL, 0xf, 0xf, true)); }
; DI void eseg_load(ESeg& r, __amdgpu_buffer_rsrc_t rs, int voff) { r.a = __builtin_amdgcn_raw_buffer_load_b128(rs, voff, 0, 0); r.b = __builtin_amdgcn_raw_buffer_load_b64(rs, voff + 16, 0, 0); }
; DI v32f eseg_unpack(const ESeg& r) { return __builtin_amdgcn_cvt_scalef32_pk32_f32_fp6((v6i){(int)r.a.x, (int)r.a.y, (int)r.a.z, (int)r.a.w, (int)r.b.x, (int)r.b.y}, 1.0f); }
; DI int id_of(const u32x4 (&d)[2], int r, unsigned mask = 0xffffu) { const unsigned w = d[r >> 3][(r >> 1) & 3]; return (r & 1) ? (int)((w >> 16) & mask) : (int)(w & mask); }
;     ...
;         for (int r = 0; r < 16; ++r) {
;             const v32f rr = eseg_unpack(rw[r]); const f32x2 w2 = {wt[r], wt[r]};
; #pragma unroll
;             for (int j = 0; j < 16; ++j) fa[j] = __builtin_elementwise_fma((f32x2){rr[2 * j], rr[2 * j + 1]}, w2, fa[j]);
;             eseg_load(rw[r], VS, id_of(idn, r, mask) * ESEG + s24);
;             if (r & 1) __builtin_amdgcn_sched_barrier(0);
;         }
;         float f16[16], f8[8];
; #pragma unroll
;         for (int j = 0; j < 16; ++j) { const float lo = (j & 1) ? fa[j >> 1].y : fa[j >> 1].x, hi = (j & 1) ? fa[8 + (j >> 1)].y : fa[8 + (j >> 1)].x;
;             const auto a = __builtin_amdgcn_permlane32_swap(__float_as_uint(lo), __float_as_uint(hi), false, false); f16[j] = __uint_as_float(a[0]) + __uint_as_float(a[1]); }
; #pragma unroll
;         for (int j = 0; j < 8; ++j) { const auto a = __builtin_amdgcn_permlane16_swap(__float_as_uint(f16[j]), __float_as_uint(f16[j + 8]), false, false); f8[j] = __uint_as_float(a[0]) + __uint_as_float(a[1]); }
; #pragma unroll
;         for (int j = 0; j < 8; ++j) f8[j] = dpp_add<0x128>(f8[j]);
;         f32x4 z;
;         z.x = ALPHA * x1.x + g2.x * (b3 ? f8[4] : f8[0]); z.y = ALPHA * x1.y + g2.y * (b3 ? f8[5] : f8[1]); z.z = ALPHA * x1.z + g2.z * (b3 ? f8[6] : f8[2]); z.w = ALPHA * x1.w + g2.w * (b3 ? f8[7] : f8[3]);
;         if (!dry) *(f32x4*)xp = z;
;         if (tn >= nrows) break;
;         t = tn; idn[0] = idnn[0]; idn[1] = idnn[1];
	v_cvt_scalef32_pk32_f32_fp6 v[0:31], v[74:79], 1.0
	v_lshrrev_b32_e32 v210, 16, v161
	v_lshl_add_u32 v211, v210, 6, v222
	v_lshl_add_u32 v210, v210, 7, v128
	v_pk_fma_f32 v[194:195], v[0:1], v[164:165], v[194:195] op_sel:[0,1,0] op_sel_hi:[1,1,1]
	v_pk_fma_f32 v[196:197], v[2:3], v[164:165], v[196:197] op_sel:[0,1,0] op_sel_hi:[1,1,1]
	v_pk_fma_f32 v[228:229], v[16:17], v[164:165], v[228:229] op_sel:[0,1,0] op_sel_hi:[1,1,1]
	v_pk_fma_f32 v[16:17], v[20:21], v[164:165], v[232:233] op_sel:[0,1,0] op_sel_hi:[1,1,1]
	v_pk_fma_f32 v[198:199], v[4:5], v[164:165], v[198:199] op_sel:[0,1,0] op_sel_hi:[1,1,1]
	v_pk_fma_f32 v[200:201], v[6:7], v[164:165], v[200:201] op_sel:[0,1,0] op_sel_hi:[1,1,1]
	v_pk_fma_f32 v[202:203], v[8:9], v[164:165], v[202:203] op_sel:[0,1,0] op_sel_hi:[1,1,1]
	v_pk_fma_f32 v[8:9], v[10:11], v[164:165], v[204:205] op_sel:[0,1,0] op_sel_hi:[1,1,1]
	v_pk_fma_f32 v[4:5], v[12:13], v[164:165], v[224:225] op_sel:[0,1,0] op_sel_hi:[1,1,1]
	v_pk_fma_f32 v[0:1], v[14:15], v[164:165], v[226:227] op_sel:[0,1,0] op_sel_hi:[1,1,1]
	v_pk_fma_f32 v[18:19], v[18:19], v[164:165], v[230:231] op_sel:[0,1,0] op_sel_hi:[1,1,1]
	v_pk_fma_f32 v[14:15], v[22:23], v[164:165], v[234:235] op_sel:[0,1,0] op_sel_hi:[1,1,1]
	v_pk_fma_f32 v[12:13], v[24:25], v[164:165], v[236:237] op_sel:[0,1,0] op_sel_hi:[1,1,1]
	v_pk_fma_f32 v[10:11], v[26:27], v[164:165], v[182:183] op_sel:[0,1,0] op_sel_hi:[1,1,1]
	v_pk_fma_f32 v[6:7], v[28:29], v[164:165], v[184:185] op_sel:[0,1,0] op_sel_hi:[1,1,1]
	v_pk_fma_f32 v[2:3], v[30:31], v[164:165], v[208:209] op_sel:[0,1,0] op_sel_hi:[1,1,1]
	buffer_load_dwordx4 v[74:77], v210, s[48:51], 0 offen
	buffer_load_dwordx2 v[78:79], v211, s[48:51], 0 offen
	v_permlane32_swap_b32_e32 v194, v228
	v_permlane32_swap_b32_e32 v195, v229
	v_permlane32_swap_b32_e32 v196, v18
	v_permlane32_swap_b32_e32 v197, v19
	v_permlane32_swap_b32_e32 v198, v16
	v_permlane32_swap_b32_e32 v199, v17
	v_permlane32_swap_b32_e32 v200, v14
	v_permlane32_swap_b32_e32 v201, v15
	v_permlane32_swap_b32_e32 v202, v12
	v_permlane32_swap_b32_e32 v203, v13
	v_permlane32_swap_b32_e32 v8, v10
	v_permlane32_swap_b32_e32 v9, v11
	v_permlane32_swap_b32_e32 v4, v6
	v_permlane32_swap_b32_e32 v5, v7
	v_permlane32_swap_b32_e32 v0, v2
	v_permlane32_swap_b32_e32 v1, v3
	v_add_f32_e32 v20, v194, v228
	v_add_f32_e32 v21, v195, v229
	v_add_f32_e32 v18, v196, v18
	v_add_f32_e32 v19, v197, v19
	v_add_f32_e32 v16, v198, v16
	v_add_f32_e32 v17, v199, v17
	v_add_f32_e32 v14, v200, v14
	v_add_f32_e32 v15, v201, v15
	v_add_f32_e32 v12, v202, v12
	v_add_f32_e32 v13, v203, v13
	v_add_f32_e32 v8, v8, v10
	v_add_f32_e32 v9, v9, v11
	v_add_f32_e32 v4, v4, v6
	v_add_f32_e32 v5, v5, v7
	v_add_f32_e32 v0, v0, v2
	v_add_f32_e32 v1, v1, v3
	v_permlane16_swap_b32_e32 v20, v12
	v_permlane16_swap_b32_e32 v21, v13
	v_permlane16_swap_b32_e32 v18, v8
	v_permlane16_swap_b32_e32 v19, v9
	v_permlane16_swap_b32_e32 v16, v4
	v_permlane16_swap_b32_e32 v17, v5
	v_permlane16_swap_b32_e32 v14, v0
	v_permlane16_swap_b32_e32 v15, v1
	v_pk_add_f32 v[2:3], v[20:21], v[12:13]
	v_pk_add_f32 v[4:5], v[16:17], v[4:5]
	v_pk_add_f32 v[8:9], v[18:19], v[8:9]
	v_pk_add_f32 v[0:1], v[14:15], v[0:1]
	v_mov_b32_dpp v6, v2 row_ror:8 row_mask:0xf bank_mask:0xf bound_ctrl:1
	v_mov_b32_dpp v7, v3 row_ror:8 row_mask:0xf bank_mask:0xf bound_ctrl:1
	v_mov_b32_dpp v10, v4 row_ror:8 row_mask:0xf bank_mask:0xf bound_ctrl:1
	v_mov_b32_dpp v11, v5 row_ror:8 row_mask:0xf bank_mask:0xf bound_ctrl:1
	v_mov_b32_dpp v12, v8 row_ror:8 row_mask:0xf bank_mask:0xf bound_ctrl:1
	v_mov_b32_dpp v13, v9 row_ror:8 row_mask:0xf bank_mask:0xf bound_ctrl:1
	v_mov_b32_dpp v14, v0 row_ror:8 row_mask:0xf bank_mask:0xf bound_ctrl:1
	v_mov_b32_dpp v15, v1 row_ror:8 row_mask:0xf bank_mask:0xf bound_ctrl:1
	v_pk_add_f32 v[8:9], v[8:9], v[12:13]
	v_pk_add_f32 v[2:3], v[2:3], v[6:7]
	v_pk_add_f32 v[4:5], v[4:5], v[10:11]
	v_pk_add_f32 v[0:1], v[0:1], v[14:15]
	v_cndmask_b32_e32 v3, v5, v3, vcc
	v_cndmask_b32_e32 v1, v1, v9, vcc
	v_cndmask_b32_e32 v0, v0, v8, vcc
	v_cndmask_b32_e32 v2, v4, v2, vcc
	s_waitcnt vmcnt(32)
	v_pk_mul_f32 v[0:1], v[172:173], v[0:1]
	v_pk_mul_f32 v[4:5], v[170:171], v[2:3]
	v_mov_b64_e32 v[158:159], v[130:131]
	v_mov_b64_e32 v[160:161], v[132:133]
	v_pk_fma_f32 v[2:3], v[168:169], s[14:15], v[0:1] op_sel_hi:[1,0,1]
	v_pk_fma_f32 v[0:1], v[166:167], s[14:15], v[4:5] op_sel_hi:[1,0,1]
	v_mov_b64_e32 v[186:187], v[134:135]
	v_mov_b64_e32 v[188:189], v[136:137]
	global_store_dwordx4 v[220:221], v[0:3], off
	v_lshl_add_u64 v[220:221], v[220:221], 0, s[8:9]
	s_or_b64 s[10:11], s[36:37], s[10:11]
	v_mov_b64_e32 v[162:163], v[138:139]
	v_mov_b64_e32 v[164:165], v[140:141]
	v_mov_b64_e32 v[174:175], v[142:143]
	v_mov_b64_e32 v[176:177], v[144:145]
	v_mov_b64_e32 v[190:191], v[146:147]
	v_mov_b64_e32 v[192:193], v[148:149]
	v_mov_b64_e32 v[178:179], v[150:151]
	v_mov_b64_e32 v[180:181], v[152:153]
	v_mov_b32_e32 v0, v250
	s_andn2_b64 exec, exec, s[10:11]
	s_cbranch_execnz .LBB0_1095
